# st1 + queue pop issued at unit end (overlaps atomic RTT with the final store drain) for prompt diff and FoX queues
# speedup vs baseline: 1.0138x; 1.0138x over previous
; #define LAS __attribute__((address_space(3)))
; template <int KIND>
; __device__ __forceinline__ void attn_queue(const AttnCtx& C, unsigned* head, int nunits, LAS unsigned char* lds) {
;     volatile LAS unsigned* slot = (volatile LAS unsigned*)(lds + AL_MISC);
;     if constexpr (KIND == 0) tuned::fox_tables(C, lds);
;     for (;;) {
;         __syncthreads();
;         if (threadIdx.x == 0) slot[0] = __hip_atomic_fetch_add(head, 1u, __ATOMIC_RELAXED, __HIP_MEMORY_SCOPE_AGENT);
;         __syncthreads();
;         const unsigned u = slot[0];
;         if (u >= (unsigned)nunits) break;
.LBB0_444:
	s_add_u32 s12, s94, 0x13c00000
	s_addc_u32 s13, s95, 0
	s_add_u32 s14, s94, 0x8000
	s_addc_u32 s15, s95, 0
	s_add_i32 s50, 0, 0x21000
	s_mov_b32 s17, 0
	v_mov_b32_e32 v3, 0
	v_mov_b32_e32 v1, s50
	s_mov_b64 s[18:19], 0x80
	s_mov_b64 s[20:21], 0x10000
	s_mov_b64 s[22:23], 0x20000
	s_movk_i32 s51, 0xff80
	s_movk_i32 s52, 0xff60
	s_mov_b64 s[24:25], 0x30000
	s_mov_b64 s[26:27], 0x10080
	s_mov_b64 s[28:29], 0x40000
	s_mov_b64 s[30:31], 0xb020000
	s_mov_b64 s[34:35], 0xb020080
	s_mov_b64 s[36:37], 0x50000
	s_mov_b64 s[38:39], 0xb030000
	s_mov_b64 s[40:41], 0xb030080
	s_mov_b64 s[42:43], 0xb010000
	s_mov_b64 s[44:45], 0xb010080
	s_movk_i32 s53, 0xff42
	s_movk_i32 s54, 0xff81
	s_movk_i32 s55, 0x7fff
	v_mov_b32_e32 v217, 0x358637bd
	s_mov_b32 s56, 0xf800000
	v_mov_b32_e32 v228, 0x260
	v_mov_b32_e32 v229, 1
	s_mov_b32 s57, 0x41000000
	v_mov_b32_e32 v18, 0xff800000
	s_mov_b32 s101, 0
	s_branch .LBB0_449

; template <int KIND>
; __device__ __forceinline__ void attn_queue(const AttnCtx& C, unsigned* head, int nunits, LAS unsigned char* lds) {
;     ...
;         __syncthreads();
;         if (threadIdx.x == 0) slot[0] = __hip_atomic_fetch_add(head, 1u, __ATOMIC_RELAXED, __HIP_MEMORY_SCOPE_AGENT);
.LBB0_449:
	s_waitcnt lgkmcnt(0)
	s_barrier
	s_mov_b64 s[2:3], exec
	v_readlane_b32 s0, v253, 26
	v_readlane_b32 s1, v253, 27
	s_and_b64 s[0:1], s[2:3], s[0:1]
	s_mov_b64 exec, s[0:1]
	s_cbranch_execz .LBB0_453
	s_mov_b64 s[6:7], exec
	v_mbcnt_lo_u32_b32 v2, s6, 0
	v_mbcnt_hi_u32_b32 v2, s7, v2
	v_cmp_eq_u32_e32 vcc, 0, v2
	s_and_saveexec_b64 s[4:5], vcc
	s_cbranch_execz .LBB0_452
	s_cmp_eq_u32 s101, 1
	s_cbranch_scc1 .LBB0_452
	v_readlane_b32 s0, v253, 2
	s_and_b32 s0, s0, 3
	s_lshl_b32 s0, s0, 8
	s_add_i32 s0, s0, 0x18000
	v_mov_b32_e32 v254, s0
	s_bcnt1_i32_b64 s0, s[6:7]
	v_mov_b32_e32 v4, s0
	global_atomic_add v4, v254, v4, s[94:95] sc0

; template <bool NOMAX>
; __device__ __forceinline__ void diff_unit(const AttnCtx& C, int u, LAS unsigned char* lds) {
;     int tid = threadIdx.x; asm volatile("" : "+v"(tid));
;     const int lane = tid & 63, r32 = lane & 31, hi = lane >> 5; const int wid = __builtin_amdgcn_readfirstlane(tid >> 6);
;     const int umap = (u >> 2) & 1, h = u & 3, qb = 63 - (u >> 3);
;     const int n = 4 * qb + 4, q0 = 256 * qb;
;     LAS float* wsf = (LAS float*)(lds + TD_WS) + wid * 64;
;     const LAS float* tab = (const LAS float*)(lds + AL_TAB) + h * 192;
;     const float c15 = tab[0];
;     const int qrel = wid * 32 + r32, qpos = q0 + qrel;
;     const int tmax = n - 4 + (wid >> 1);
;     __syncthreads();
;     const bf16* Qw = C.DQ + (size_t)(q0 + wid * 32) * 512 + h * 128 + umap * 64;
;     const bf16* Kh = C.DK + h * 128 + umap * 64; const bf16* Vh = C.DV + h * 128;
;     const unsigned lds0 = (unsigned)(size_t)lds;
;     const bf16* ksrc = Kh + (size_t)lane * 512 + wid * 8;
;     const bf16* vsrc = Vh + (size_t)(16 * (wid & 3) + (lane >> 2)) * 512 + (wid >> 2) * 32 + (lane & 3) * 8;
;     const unsigned kdst = lds0 + TD_K + wid * 1024, vdst = lds0 + TD_V + wid * 1024;
;     ...
;     const lcp kp0 = (lcp)(lds + TD_K) + hi * 1024 + r32 * 16;
;     const lcp vp0 = (lcp)(lds + TD_V) + ((lane >> 4) & 1) * 32 + (lane & 3) * 8 + (4 * hi + ((lane & 15) >> 2)) * 64;
;     bf16x8 kf[8];
;     DMA_K(0, 0); DMA_V(0, 0); DMA_K(1, SLOTB);
;     const lcp qp0 = (lcp)(lds + TD_Q) + wid * 4096 + lane * 16;
;     {
;         bf16x8 qr[4];
; #pragma unroll
;         for (int d0 = 0; d0 < 4; ++d0) qr[d0] = *(const bf16x8*)(Qw + (size_t)r32 * 512 + d0 * 16 + hi * 8);
; #pragma unroll
;         for (int d0 = 0; d0 < 4; ++d0) *(LAS bf16x8*)((LAS unsigned char*)qp0 + d0 * 1024) = qr[d0];
;     }
;     ...
;     float nm = c15, l_reg = 0.f;
;     f32x16 o[4];
; #pragma unroll
;     for (int d = 0; d < 4; ++d) o[d] = (f32x16){0.f,0.f,0.f,0.f,0.f,0.f,0.f,0.f,0.f,0.f,0.f,0.f,0.f,0.f,0.f,0.f};
;     bool resc = false;
;     ...
;     f32x16 pA0, pA1, pB0, pB1;
;     const f32x16 ZERO16 = (f32x16){0.f,0.f,0.f,0.f,0.f,0.f,0.f,0.f,0.f,0.f,0.f,0.f,0.f,0.f,0.f,0.f};
;     int sl_prev = 0, sl_cur = 0, sl_next = 1;
;     ...
;     DMA_K(2, 2 * SLOTB);
;     TWAIT_BAR(4);
;     {
;         if constexpr (NOMAX) { pA0 = (f32x16){0.f,0.f,0.f,0.f,0.f,0.f,0.f,0.f,0.f,0.f,0.f,0.f,0.f,0.f,0.f,0.f}; pA1 = pA0; } else { INITC(pA0, pA1); }
.LBB0_453:
	s_or_b64 exec, exec, s[2:3]
	s_mov_b32 s101, 0
	s_waitcnt lgkmcnt(0)
	s_barrier
	ds_read_b32 v2, v1
	s_movk_i32 s0, 0x7f
	s_mov_b64 s[2:3], -1
	s_waitcnt lgkmcnt(0)
	v_cmp_lt_u32_e32 vcc, s0, v2
	s_cbranch_vccnz .LBB0_448
	v_readlane_b32 s0, v253, 2
	s_and_b32 s0, s0, 3
	v_lshrrev_b32_e32 v254, 1, v2
	v_and_b32_e32 v2, 1, v2
	v_lshlrev_b32_e32 v2, 2, v2
	v_lshl_or_b32 v2, v254, 3, v2
	v_or_b32_e32 v2, s0, v2
	v_lshlrev_b32_e32 v4, 1, v2
	v_and_b32_e32 v4, 6, v4
	v_bfe_u32 v230, v2, 2, 1
	v_and_b32_e32 v231, 3, v2
	s_movk_i32 s0, 0x300
	v_or_b32_e32 v4, v4, v230
	v_lshrrev_b32_e32 v7, 3, v2
	v_mul_lo_u32 v2, v231, s0
	v_readlane_b32 s0, v253, 56
	v_lshrrev_b32_e32 v4, v4, v233
	v_lshlrev_b32_e32 v220, 8, v231
	v_mov_b32_e32 v221, v3
	v_readlane_b32 s1, v253, 57
	v_and_b32_e32 v6, 1, v4
	v_add_u32_e32 v2, 0, v2
	v_lshl_add_u64 v[4:5], s[0:1], 0, v[220:221]
	v_readlane_b32 s0, v253, 58
	v_xor_b32_e32 v224, 63, v7
	v_add_u32_e32 v235, 0x20400, v2
	v_lshlrev_b32_e32 v8, 7, v231
	v_lshlrev_b32_e32 v9, 6, v230
	v_lshlrev_b32_e32 v2, 7, v230
	v_readlane_b32 s1, v253, 59
	v_cmp_eq_u32_e32 vcc, 0, v6
	v_lshlrev_b32_e32 v234, 2, v224
	v_lshlrev_b32_e32 v19, 8, v224
	v_lshl_add_u64 v[198:199], v[4:5], 0, v[2:3]
	v_lshl_add_u64 v[196:197], s[0:1], 0, v[220:221]
	v_cmp_ne_u32_e64 s[2:3], 63, v7
	v_lshlrev_b32_e32 v218, 1, v8
	v_lshlrev_b32_e32 v200, 1, v9
	s_cbranch_vccnz .LBB0_465
	v_mov_b32_e32 v6, v0
	v_readlane_b32 s4, v253, 54
	v_readfirstlane_b32 s1, v6
	s_ashr_i32 s6, s1, 6
	s_lshl_b32 s33, s6, 5
	v_add_u32_e32 v202, s33, v19
	v_ashrrev_i32_e32 v203, 31, v202
	v_lshlrev_b64 v[4:5], 10, v[202:203]
	v_readlane_b32 s5, v253, 55
	v_and_b32_e32 v212, 63, v6
	v_mov_b32_e32 v219, v3
	v_lshl_add_u64 v[4:5], s[4:5], 0, v[4:5]
	v_lshl_add_u64 v[4:5], v[4:5], 0, v[218:219]
	v_mov_b32_e32 v201, v3
	v_lshlrev_b32_e32 v2, 10, v212
	s_lshl_b32 s0, s6, 4
	v_bfe_u32 v208, v6, 2, 4
	v_lshl_add_u64 v[8:9], v[4:5], 0, v[200:201]
	v_lshl_add_u64 v[4:5], v[198:199], 0, v[2:3]
	s_lshl_b32 s4, s6, 3
	v_and_or_b32 v2, s0, 48, v208
	s_ashr_i32 s5, s4, 31
	v_lshlrev_b32_e32 v2, 10, v2
	s_ashr_i32 s0, s1, 3
	v_lshl_add_u64 v[204:205], s[4:5], 1, v[4:5]
	v_lshl_add_u64 v[4:5], v[196:197], 0, v[2:3]
	s_and_b32 s4, s0, 0xffffffe0
	v_lshlrev_b32_e32 v2, 3, v6
	s_ashr_i32 s5, s4, 31
	v_and_b32_e32 v7, 24, v2
	s_lshl_b32 s49, s6, 10
	v_and_b32_e32 v210, 31, v6
	ds_read_b32 v213, v235
	s_waitcnt lgkmcnt(0)
	s_barrier
	v_lshl_add_u64 v[4:5], s[4:5], 1, v[4:5]
	v_lshlrev_b32_e32 v2, 1, v7
	s_add_i32 s49, s49, 0
	s_mov_b32 s0, m0
	s_mov_b32 m0, s49
	s_nop 0
	global_load_lds_dwordx4 v[204:205], off
	s_mov_b32 m0, s0
	v_bfe_u32 v211, v6, 5, 1
	v_lshl_add_u64 v[4:5], v[4:5], 0, v[2:3]
	s_add_i32 s58, s49, 0x6000
	s_mov_b32 s0, m0
	s_mov_b32 m0, s58
	s_nop 0
	global_load_lds_dwordx4 v[4:5], off
	s_mov_b32 m0, s0
	v_lshlrev_b32_e32 v2, 10, v210
	v_lshl_add_u64 v[10:11], v[4:5], 0, s[18:19]
	s_add_i32 s0, s49, 0x8000
	s_mov_b32 s7, m0
	s_mov_b32 m0, s0
	s_nop 0
	global_load_lds_dwordx4 v[10:11], off
	s_mov_b32 m0, s7
	v_lshl_add_u64 v[8:9], v[8:9], 0, v[2:3]
	v_lshlrev_b32_e32 v2, 4, v211
	v_lshl_add_u64 v[10:11], v[204:205], 0, s[20:21]
	s_add_i32 s0, s49, 0x2000
	s_mov_b32 s7, m0
	s_mov_b32 m0, s0
	s_nop 0
	global_load_lds_dwordx4 v[10:11], off
	s_mov_b32 m0, s7
	v_lshl_add_u64 v[16:17], v[8:9], 0, v[2:3]
	global_load_dwordx4 v[8:11], v[16:17], off
	global_load_dwordx4 v[12:15], v[16:17], off offset:32
	global_load_dwordx4 v[20:23], v[16:17], off offset:64
	global_load_dwordx4 v[24:27], v[16:17], off offset:96
	s_lshl_b32 s0, s6, 12
	s_add_i32 s7, s0, 0
	v_lshlrev_b32_e32 v16, 4, v212
	s_add_i32 s7, s7, 0x12800
	v_add_u32_e32 v219, s7, v16
	v_lshlrev_b32_e32 v201, 10, v211
	v_lshlrev_b32_e32 v2, 4, v210
	s_add_i32 s8, s49, 0x4000
	v_lshl_add_u64 v[16:17], v[204:205], 0, s[22:23]
	v_add3_u32 v222, 0, v201, v2
	s_ashr_i32 s48, s1, 7
	v_or_b32_e32 v2, s33, v210
	s_and_b64 vcc, exec, s[2:3]
	v_add_u32_e32 v223, s48, v234
	v_add_u32_e32 v215, v2, v19
	s_waitcnt vmcnt(3)
	ds_write_b128 v219, v[8:11]
	s_waitcnt vmcnt(2)
	ds_write_b128 v219, v[12:15] offset:1024
	s_waitcnt vmcnt(1)
	ds_write_b128 v219, v[20:23] offset:2048
	s_waitcnt vmcnt(0)
	ds_write_b128 v219, v[24:27] offset:3072
	s_mov_b32 s7, m0
	s_mov_b32 m0, s8
	s_nop 0
	global_load_lds_dwordx4 v[16:17], off
	s_mov_b32 m0, s7
	s_waitcnt vmcnt(4) lgkmcnt(0)
	s_barrier
	ds_read_b128 v[8:11], v222
	ds_read_b128 v[12:15], v219
	s_waitcnt lgkmcnt(0)
	v_mfma_f32_32x32x16_bf16 v[36:51], v[8:11], v[12:15], 0
	ds_read_b128 v[8:11], v222 offset:512
	s_waitcnt lgkmcnt(0)
	v_mfma_f32_32x32x16_bf16 v[20:35], v[8:11], v[12:15], 0
	ds_read_b128 v[8:11], v222 offset:2048
	ds_read_b128 v[12:15], v219 offset:1024
	s_waitcnt lgkmcnt(0)
	v_mfma_f32_32x32x16_bf16 v[36:51], v[8:11], v[12:15], v[36:51]
	ds_read_b128 v[8:11], v222 offset:2560
	s_waitcnt lgkmcnt(0)
	v_mfma_f32_32x32x16_bf16 v[20:35], v[8:11], v[12:15], v[20:35]
	ds_read_b128 v[8:11], v222 offset:4096
	ds_read_b128 v[12:15], v219 offset:2048
	s_waitcnt lgkmcnt(0)
	v_mfma_f32_32x32x16_bf16 v[36:51], v[8:11], v[12:15], v[36:51]
	ds_read_b128 v[8:11], v222 offset:4608
	s_waitcnt lgkmcnt(0)
	v_mfma_f32_32x32x16_bf16 v[20:35], v[8:11], v[12:15], v[20:35]
	ds_read_b128 v[8:11], v222 offset:6144
	ds_read_b128 v[12:15], v219 offset:3072
	s_waitcnt lgkmcnt(0)
	v_mfma_f32_32x32x16_bf16 v[36:51], v[8:11], v[12:15], v[36:51]
	ds_read_b128 v[8:11], v222 offset:6656
	s_waitcnt lgkmcnt(0)
	v_mfma_f32_32x32x16_bf16 v[20:35], v[8:11], v[12:15], v[20:35]
	s_cbranch_vccnz .LBB0_461
; #define LAS __attribute__((address_space(3)))
; #define TWAIT_BAR(N) asm volatile("s_waitcnt vmcnt(" #N ") lgkmcnt(0)\n\ts_barrier" ::: "memory")
; #define DMA_K(t, slot) glds16(ksrc + (size_t)(t) * 64 * 512, (unsigned)__builtin_amdgcn_readfirstlane(kdst + (slot)))
; #define DMA_K(t, slot) glds16(ksrc + (size_t)(t) * 64 * 512, (unsigned)__builtin_amdgcn_readfirstlane(kdst + (slot)))
; #define INITC(P0, P1) do { _Pragma("unroll") for (int r_ = 0; r_ < 16; ++r_) { P0[r_] = nm; P1[r_] = nm; } } while (0)
; #define INITC(P0, P1) do { _Pragma("unroll") for (int r_ = 0; r_ < 16; ++r_) { P0[r_] = nm; P1[r_] = nm; } } while (0)
; #define NEARK(P0, P1, kk) do { if ((kk) >= 62) _Pragma("unroll") for (int r_ = 0; r_ < 16; ++r_) { const int rel0 = (kk) * 64 + crow(r_, hi) - qpos; int i0 = rel0 < -128 ? -128 : rel0; i0 = i0 > 63 ? 63 : i0; int i1 = rel0 + 32 < -128 ? -128 : rel0 + 32; i1 = i1 > 63 ? 63 : i1; \
;             P0[r_] += tab[i0 + 128] - c15; P1[r_] += tab[i1 + 128] - c15; } } while (0)
; template <bool NOMAX>
; __device__ __forceinline__ void diff_unit(const AttnCtx& C, int u, LAS unsigned char* lds) {
;     ...
;     f32x16 pA0, pA1, pB0, pB1;
;     const f32x16 ZERO16 = (f32x16){0.f,0.f,0.f,0.f,0.f,0.f,0.f,0.f,0.f,0.f,0.f,0.f,0.f,0.f,0.f,0.f};
;     int sl_prev = 0, sl_cur = 0, sl_next = 1;
;     ...
;     DMA_K(2, 2 * SLOTB);
;     TWAIT_BAR(4);
;     {
;         if constexpr (NOMAX) { pA0 = (f32x16){0.f,0.f,0.f,0.f,0.f,0.f,0.f,0.f,0.f,0.f,0.f,0.f,0.f,0.f,0.f,0.f}; pA1 = pA0; } else { INITC(pA0, pA1); }
;         const lcp kb = kp0;
; #pragma unroll
;         for (int d0 = 0; d0 < 4; ++d0) { const bf16x8 b0 = *(const LAS bf16x8*)(kb + d0 * 2048), b1 = *(const LAS bf16x8*)(kb + d0 * 2048 + 512);
;             const bf16x8 qv = QRD(d0); pA0 = __builtin_amdgcn_mfma_f32_32x32x16_bf16(b0, qv, pA0, 0, 0, 0); pA1 = __builtin_amdgcn_mfma_f32_32x32x16_bf16(b1, qv, pA1, 0, 0, 0); }
;         NEARK(pA0, pA1, 0);
	v_cmp_gt_i32_e32 vcc, 0, v223
	v_mov_b32_e32 v2, 0xff800000
	s_and_b64 vcc, exec, vcc
	v_mov_b32_e32 v8, 0xff800000
	v_mov_b32_e32 v9, 0xff800000
	v_mov_b32_e32 v10, 0xff800000
	v_mov_b32_e32 v11, 0xff800000
	v_mov_b32_e32 v12, 0xff800000
	v_mov_b32_e32 v13, 0xff800000
	v_mov_b32_e32 v14, 0xff800000
	v_mov_b32_e32 v15, 0xff800000
	v_mov_b32_e32 v16, 0xff800000
	v_mov_b32_e32 v17, 0xff800000
	v_mov_b32_e32 v52, 0xff800000
	v_mov_b32_e32 v53, 0xff800000
	v_mov_b32_e32 v54, 0xff800000
	v_mov_b32_e32 v55, 0xff800000
	v_mov_b32_e32 v56, 0xff800000
	v_mov_b32_e32 v57, 0xff800000
	v_mov_b32_e32 v58, 0xff800000
	v_mov_b32_e32 v59, 0xff800000
	v_mov_b32_e32 v60, 0xff800000
	v_mov_b32_e32 v61, 0xff800000
	v_mov_b32_e32 v62, 0xff800000
	v_mov_b32_e32 v63, 0xff800000
	v_mov_b32_e32 v64, 0xff800000
	v_mov_b32_e32 v65, 0xff800000
	v_mov_b32_e32 v66, 0xff800000
	v_mov_b32_e32 v67, 0xff800000
	v_mov_b32_e32 v68, 0xff800000
	v_mov_b32_e32 v69, 0xff800000
	v_mov_b32_e32 v70, 0xff800000
	v_mov_b32_e32 v71, 0xff800000
	v_mov_b32_e32 v72, 0xff800000
	s_cbranch_vccnz .LBB0_460
	s_cmp_gt_i32 s6, 5
	s_cbranch_scc1 .LBB0_459
	v_lshlrev_b32_e32 v2, 2, v211
	v_sub_u32_e32 v2, v2, v215
	v_add_u32_e32 v10, 1, v2
	v_add_u32_e32 v12, 2, v2
	v_add_u32_e32 v14, 3, v2
	v_med3_i32 v8, v2, s51, 63
	v_med3_i32 v9, v2, s52, 31
	v_med3_i32 v11, v10, s51, 63
	v_med3_i32 v10, v10, s52, 31
	v_med3_i32 v13, v12, s51, 63
	v_med3_i32 v12, v12, s52, 31
	v_med3_i32 v15, v14, s51, 63
	v_med3_i32 v14, v14, s52, 31
	v_lshl_add_u32 v8, v8, 2, v235
	v_lshl_add_u32 v9, v9, 2, v235
	v_lshl_add_u32 v11, v11, 2, v235
	v_lshl_add_u32 v10, v10, 2, v235
	v_lshl_add_u32 v12, v12, 2, v235
	v_lshl_add_u32 v14, v14, 2, v235
	v_lshl_add_u32 v13, v13, 2, v235
	v_lshl_add_u32 v15, v15, 2, v235
	ds_read_b32 v8, v8 offset:512
	ds_read_b32 v58, v9 offset:640
	ds_read_b32 v9, v11 offset:512
	ds_read_b32 v59, v10 offset:640
	ds_read_b32 v10, v13 offset:512
	ds_read_b32 v60, v12 offset:640
	ds_read_b32 v11, v15 offset:512
	ds_read_b32 v61, v14 offset:640
	v_add_u32_e32 v12, 8, v2
	v_add_u32_e32 v14, 9, v2
	v_add_u32_e32 v16, 10, v2
	v_add_u32_e32 v52, 11, v2
	v_med3_i32 v13, v12, s51, 63
	v_med3_i32 v12, v12, s52, 31
	v_med3_i32 v15, v14, s51, 63
	v_med3_i32 v14, v14, s52, 31
	v_med3_i32 v17, v16, s51, 63
	v_med3_i32 v53, v52, s51, 63
	v_lshl_add_u32 v13, v13, 2, v235
	v_lshl_add_u32 v12, v12, 2, v235
	v_lshl_add_u32 v15, v15, 2, v235
	v_lshl_add_u32 v14, v14, 2, v235
	v_med3_i32 v16, v16, s52, 31
	v_lshl_add_u32 v17, v17, 2, v235
	v_med3_i32 v52, v52, s52, 31
	v_lshl_add_u32 v53, v53, 2, v235
	v_lshl_add_u32 v16, v16, 2, v235
	v_lshl_add_u32 v52, v52, 2, v235
	ds_read_b32 v54, v13 offset:512
	ds_read_b32 v62, v12 offset:640
	ds_read_b32 v12, v15 offset:512
	ds_read_b32 v63, v14 offset:640
	ds_read_b32 v14, v17 offset:512
	ds_read_b32 v64, v16 offset:640
	ds_read_b32 v15, v53 offset:512
	ds_read_b32 v65, v52 offset:640
	v_add_u32_e32 v13, 16, v2
	v_add_u32_e32 v17, 17, v2
	v_add_u32_e32 v53, 18, v2
	v_med3_i32 v16, v13, s51, 63
	v_med3_i32 v13, v13, s52, 31
	v_med3_i32 v52, v17, s51, 63
	v_med3_i32 v55, v53, s51, 63
	v_med3_i32 v53, v53, s52, 31
	v_add_u32_e32 v56, 19, v2
	v_lshl_add_u32 v16, v16, 2, v235
	v_lshl_add_u32 v13, v13, 2, v235
	v_med3_i32 v17, v17, s52, 31
	v_lshl_add_u32 v52, v52, 2, v235
	v_lshl_add_u32 v55, v55, 2, v235
	v_lshl_add_u32 v53, v53, 2, v235
	v_med3_i32 v57, v56, s51, 63
	v_med3_i32 v56, v56, s52, 31
	v_lshl_add_u32 v17, v17, 2, v235
	v_lshl_add_u32 v57, v57, 2, v235
	v_lshl_add_u32 v56, v56, 2, v235
	ds_read_b32 v16, v16 offset:512
	ds_read_b32 v66, v13 offset:640
	ds_read_b32 v52, v52 offset:512
	ds_read_b32 v67, v17 offset:640
	ds_read_b32 v55, v55 offset:512
	ds_read_b32 v68, v53 offset:640
	ds_read_b32 v53, v57 offset:512
	ds_read_b32 v69, v56 offset:640
	v_add_u32_e32 v13, 24, v2
	v_med3_i32 v17, v13, s51, 63
	v_med3_i32 v13, v13, s52, 31
	v_lshl_add_u32 v57, v13, 2, v235
	v_add_u32_e32 v13, 25, v2
	v_lshl_add_u32 v56, v17, 2, v235
	v_med3_i32 v17, v13, s51, 63
	v_med3_i32 v13, v13, s52, 31
	v_lshl_add_u32 v71, v13, 2, v235
	v_add_u32_e32 v13, 26, v2
	v_lshl_add_u32 v70, v17, 2, v235
	v_med3_i32 v17, v13, s51, 63
	v_med3_i32 v13, v13, s52, 31
	v_add_u32_e32 v2, 27, v2
	v_lshl_add_u32 v73, v13, 2, v235
	v_med3_i32 v13, v2, s51, 63
	v_med3_i32 v2, v2, s52, 31
	v_lshl_add_u32 v2, v2, 2, v235
	v_lshl_add_u32 v72, v17, 2, v235
	v_lshl_add_u32 v74, v13, 2, v235
	s_waitcnt lgkmcnt(13)
	v_sub_f32_e32 v13, v12, v213
	v_sub_f32_e32 v12, v54, v213
	s_waitcnt lgkmcnt(5)
	v_sub_f32_e32 v17, v52, v213
	s_waitcnt lgkmcnt(3)
	v_sub_f32_e32 v52, v55, v213
	ds_read_b32 v54, v56 offset:512
	ds_read_b32 v75, v57 offset:640
	ds_read_b32 v55, v70 offset:512
	ds_read_b32 v70, v71 offset:640
	ds_read_b32 v56, v72 offset:512
	ds_read_b32 v57, v74 offset:512
	ds_read_b32 v2, v2 offset:640
	ds_read_b32 v71, v73 offset:640
	v_sub_f32_e32 v8, v8, v213
	v_sub_f32_e32 v9, v9, v213
	v_sub_f32_e32 v11, v11, v213
	v_sub_f32_e32 v10, v10, v213
	v_sub_f32_e32 v15, v15, v213
	v_sub_f32_e32 v14, v14, v213
	v_sub_f32_e32 v16, v16, v213
	s_waitcnt lgkmcnt(9)
	v_sub_f32_e32 v53, v53, v213
	s_waitcnt lgkmcnt(5)
	v_sub_f32_e32 v55, v55, v213
	v_sub_f32_e32 v54, v54, v213
	s_waitcnt lgkmcnt(2)
	v_sub_f32_e32 v57, v57, v213
	v_sub_f32_e32 v56, v56, v213
	v_pk_add_f32 v[50:51], v[50:51], v[56:57]
	v_pk_add_f32 v[48:49], v[48:49], v[54:55]
	v_pk_add_f32 v[46:47], v[46:47], v[52:53]
	v_pk_add_f32 v[44:45], v[44:45], v[16:17]
	v_pk_add_f32 v[42:43], v[42:43], v[14:15]
	v_pk_add_f32 v[40:41], v[40:41], v[12:13]
	v_pk_add_f32 v[38:39], v[38:39], v[10:11]
	v_pk_add_f32 v[36:37], v[36:37], v[8:9]
	v_sub_f32_e32 v8, v58, v213
	v_sub_f32_e32 v9, v59, v213
	v_sub_f32_e32 v11, v61, v213
	v_sub_f32_e32 v10, v60, v213
	v_sub_f32_e32 v13, v63, v213
	v_sub_f32_e32 v12, v62, v213
	v_sub_f32_e32 v15, v65, v213
	v_sub_f32_e32 v14, v64, v213
	v_sub_f32_e32 v17, v67, v213
	v_sub_f32_e32 v16, v66, v213
	v_sub_f32_e32 v53, v69, v213
	v_sub_f32_e32 v52, v68, v213
	v_sub_f32_e32 v55, v70, v213
	v_sub_f32_e32 v54, v75, v213
	s_waitcnt lgkmcnt(1)
	v_sub_f32_e32 v57, v2, v213
	s_waitcnt lgkmcnt(0)
	v_sub_f32_e32 v56, v71, v213
	v_pk_add_f32 v[34:35], v[34:35], v[56:57]
	v_pk_add_f32 v[32:33], v[32:33], v[54:55]
	v_pk_add_f32 v[30:31], v[30:31], v[52:53]
	v_pk_add_f32 v[28:29], v[28:29], v[16:17]
	v_pk_add_f32 v[26:27], v[26:27], v[14:15]
	v_pk_add_f32 v[24:25], v[24:25], v[12:13]
	v_pk_add_f32 v[22:23], v[22:23], v[10:11]
	v_pk_add_f32 v[20:21], v[20:21], v[8:9]

; template <bool NOMAX>
; __device__ __forceinline__ void diff_unit(const AttnCtx& C, int u, LAS unsigned char* lds) {
;     ...
;     asm volatile("s_waitcnt vmcnt(0) lgkmcnt(0)\n\ts_barrier" ::: "memory");
; template <int KIND>
; __device__ __forceinline__ void attn_queue(const AttnCtx& C, unsigned* head, int nunits, LAS unsigned char* lds) {
;     ...
;         __syncthreads();
;         if (threadIdx.x == 0) slot[0] = __hip_atomic_fetch_add(head, 1u, __ATOMIC_RELAXED, __HIP_MEMORY_SCOPE_AGENT);
.LBB0_537:
	s_mov_b64 s[98:99], exec
	v_readlane_b32 s0, v253, 26
	v_readlane_b32 s1, v253, 27
	s_and_b64 s[0:1], s[98:99], s[0:1]
	s_mov_b64 exec, s[0:1]
	s_cbranch_execz .Lpp_d_skip
	v_readlane_b32 s0, v253, 2
	s_and_b32 s0, s0, 3
	s_lshl_b32 s0, s0, 8
	s_add_i32 s0, s0, 0x18000
	v_mov_b32_e32 v254, s0
	v_mov_b32_e32 v4, 1
	global_atomic_add v4, v254, v4, s[94:95] sc0
.Lpp_d_skip:
	s_mov_b64 exec, s[98:99]
	s_mov_b32 s101, 1
	s_waitcnt vmcnt(0) lgkmcnt(0)
	s_barrier
	s_branch .LBB0_447

; #define LAS __attribute__((address_space(3)))
; __device__ __forceinline__ unsigned ldu(const unsigned* p) { return __hip_atomic_load(p, __ATOMIC_RELAXED, __HIP_MEMORY_SCOPE_AGENT); }
; __device__ __forceinline__ void fox_tables(const AttnCtx& C, LAS unsigned char* lds) {
;     int tid = threadIdx.x; asm volatile("" : "+v"(tid));
;     const int lane = tid & 63; const int wid = __builtin_amdgcn_readfirstlane(tid >> 6);
;     LAS float* PRE = (LAS float*)(lds + FX_PRE); LAS float* LQ0 = (LAS float*)(lds + FX_LQ0); LAS float* NRMF = (LAS float*)(lds + FX_NRM);
;     __syncthreads();
;     {
;         float v[4]; float run = 0.f;
; #pragma unroll
;         for (int j = 0; j < 4; ++j) { v[j] = C.TTOT[(4 * lane + j) * 8 + wid]; }
;         float loc[4];
; #pragma unroll
;         for (int j = 0; j < 4; ++j) { loc[j] = run; run += v[j]; }
;         float incl = run;
; #pragma unroll
;         for (int o = 1; o < 64; o <<= 1) { const float t = __shfl_up(incl, o); if (lane >= o) incl += t; }
;         const float excl = incl - run;
; #pragma unroll
;         for (int j = 0; j < 4; ++j) PRE[wid * FX_PST + 4 * lane + j] = excl + loc[j];
;         if (lane == 63) PRE[wid * FX_PST + 256] = incl;
;     }
;     LQ0[tid] = C.LCUM[(size_t)((tid >> 3) * 256) * 8 + (tid & 7)];
;     if (tid < 32) NRMF[tid] = __uint_as_float(ldu(C.nrm + tid));
;     asm volatile("s_waitcnt vmcnt(0) lgkmcnt(0)" ::: "memory");
;     __syncthreads();
.LBB0_801:
	s_mov_b32 s101, 0
	v_mov_b32_e32 v2, v0
	v_readlane_b32 s2, v252, 0
	v_readfirstlane_b32 s0, v2
	v_and_b32_e32 v3, 63, v2
	s_ashr_i32 s0, s0, 6
	v_lshl_add_u32 v4, v3, 5, s0
	v_ashrrev_i32_e32 v5, 31, v4
	v_readlane_b32 s3, v252, 1
	s_barrier
	s_nop 0
	v_lshl_add_u64 v[4:5], v[4:5], 2, s[2:3]
	global_load_dword v1, v[4:5], off
	global_load_dword v6, v[4:5], off offset:32
	global_load_dword v7, v[4:5], off offset:64
	global_load_dword v10, v[4:5], off offset:96
	v_mbcnt_hi_u32_b32 v11, -1, v232
	v_and_b32_e32 v12, 64, v11
	v_add_u32_e32 v5, -1, v11
	v_cmp_lt_i32_e32 vcc, v5, v12
	s_mulk_i32 s0, 0x410
	s_add_i32 s0, s0, 0
	v_cndmask_b32_e32 v5, v5, v11, vcc
	v_lshlrev_b32_e32 v13, 2, v5
	s_add_i32 s0, s0, 0x22800
	v_mov_b32_e32 v4, 0
	s_waitcnt vmcnt(3)
	v_add_f32_e32 v5, 0, v1
	s_waitcnt vmcnt(2)
	v_add_f32_e32 v8, v5, v6
	s_waitcnt vmcnt(1)
	v_add_f32_e32 v9, v8, v7
	s_waitcnt vmcnt(0)
	v_add_f32_e32 v6, v9, v10
	ds_bpermute_b32 v1, v13, v6
	v_add_u32_e32 v7, -2, v11
	v_cmp_lt_i32_e32 vcc, v7, v12
	v_add_u32_e32 v10, -4, v11
	s_waitcnt lgkmcnt(0)
	v_add_f32_e32 v1, v6, v1
	v_cndmask_b32_e32 v7, v7, v11, vcc
	v_cmp_eq_u32_e32 vcc, 0, v3
	v_lshlrev_b32_e32 v7, 2, v7
	s_nop 0
	v_cndmask_b32_e32 v1, v1, v6, vcc
	ds_bpermute_b32 v7, v7, v1
	v_cmp_lt_i32_e32 vcc, v10, v12
	s_waitcnt lgkmcnt(0)
	v_add_f32_e32 v7, v1, v7
	v_cndmask_b32_e32 v10, v10, v11, vcc
	v_cmp_gt_u32_e32 vcc, 2, v3
	v_lshlrev_b32_e32 v10, 2, v10
	s_nop 0
	v_cndmask_b32_e32 v1, v7, v1, vcc
	ds_bpermute_b32 v7, v10, v1
	v_add_u32_e32 v10, -8, v11
	v_cmp_lt_i32_e32 vcc, v10, v12
	s_waitcnt lgkmcnt(0)
	v_add_f32_e32 v7, v1, v7
	v_cndmask_b32_e32 v10, v10, v11, vcc
	v_cmp_gt_u32_e32 vcc, 4, v3
	v_lshlrev_b32_e32 v10, 2, v10
	s_nop 0
	v_cndmask_b32_e32 v1, v7, v1, vcc
	ds_bpermute_b32 v7, v10, v1
	v_add_u32_e32 v10, -16, v11
	v_cmp_lt_i32_e32 vcc, v10, v12
	s_waitcnt lgkmcnt(0)
	v_add_f32_e32 v7, v1, v7
	v_cndmask_b32_e32 v10, v10, v11, vcc
	v_cmp_gt_u32_e32 vcc, 8, v3
	v_lshlrev_b32_e32 v10, 2, v10
	s_nop 0
	v_cndmask_b32_e32 v1, v7, v1, vcc
	ds_bpermute_b32 v7, v10, v1
	v_subrev_u32_e32 v10, 32, v11
	v_cmp_lt_i32_e32 vcc, v10, v12
	s_waitcnt lgkmcnt(0)
	v_add_f32_e32 v7, v1, v7
	v_cndmask_b32_e32 v10, v10, v11, vcc
	v_cmp_gt_u32_e32 vcc, 16, v3
	v_lshlrev_b32_e32 v10, 2, v10
	v_lshl_add_u32 v11, v3, 4, s0
	v_cndmask_b32_e32 v7, v7, v1, vcc
	ds_bpermute_b32 v1, v10, v7
	v_cmp_gt_u32_e32 vcc, 32, v3
	s_waitcnt lgkmcnt(0)
	v_add_f32_e32 v1, v7, v1
	v_cndmask_b32_e32 v7, v1, v7, vcc
	v_sub_f32_e32 v10, v7, v6
	v_pk_add_f32 v[6:7], v[10:11], v[4:5] op_sel_hi:[0,1]
	v_pk_add_f32 v[8:9], v[8:9], v[10:11] op_sel_hi:[1,0]
	v_cmp_eq_u32_e32 vcc, 63, v3
	ds_write_b128 v11, v[6:9]
	s_and_saveexec_b64 s[2:3], vcc
	v_mov_b32_e32 v3, s0
	ds_write_b32 v3, v1 offset:1024
	s_or_b64 exec, exec, s[2:3]
	v_lshlrev_b32_e32 v1, 5, v2
	v_and_b32_e32 v6, 0xffffff00, v1
	v_ashrrev_i32_e32 v7, 31, v6
	v_readlane_b32 s0, v253, 62
	v_and_b32_e32 v1, 7, v2
	v_lshlrev_b64 v[6:7], 5, v[6:7]
	v_readlane_b32 s1, v253, 63
	v_lshlrev_b32_e32 v8, 2, v1
	v_mov_b32_e32 v9, v4
	v_lshl_add_u64 v[6:7], s[0:1], 0, v[6:7]
	v_lshl_add_u64 v[4:5], v[6:7], 0, v[8:9]
	global_load_dword v3, v[4:5], off
	v_lshl_add_u32 v1, v2, 2, 0
	s_mov_b32 s77, 0
	v_add_u32_e32 v4, 0x24880, v1
	v_cmp_gt_i32_e32 vcc, 32, v2
	s_waitcnt vmcnt(0)
	ds_write_b32 v4, v3
	s_and_saveexec_b64 s[2:3], vcc
	s_cbranch_execz .LBB0_805
	v_ashrrev_i32_e32 v3, 31, v2
	v_lshl_add_u64 v[2:3], v[2:3], 2, s[94:95]
	global_load_dword v2, v[2:3], off offset:2048 sc1
	v_add_u32_e32 v1, 0x25080, v1
	s_waitcnt vmcnt(0)
	ds_write_b32 v1, v2

; #define LAS __attribute__((address_space(3)))
; __device__ __forceinline__ unsigned f2bf(float f) { unsigned u = __builtin_bit_cast(unsigned, f); return (u + 0x7fffu + ((u >> 16) & 1u)) >> 16; }
; __device__ __forceinline__ int crow(int r, int hi) { return (r & 3) + 8 * (r >> 2) + 4 * hi; }
; template <bool NOMAX>
; __device__ __forceinline__ void fox_unit(const AttnCtx& C, int u, LAS unsigned char* lds) {
;     ...
;     asm volatile("s_waitcnt lgkmcnt(0)\n\ts_barrier" ::: "memory");
;     float rli[16];
; #pragma unroll
;     for (int r = 0; r < 16; ++r) rli[r] = __builtin_amdgcn_rcpf(wsf[32 + crow(r, hi)]);
;     {
;         LAS bf16* stg = (LAS bf16*)(lds + TF_OST) + wid * 2048;
; #pragma unroll
;         for (int r = 0; r < 16; ++r) { const int orow = crow(r, hi);
; #pragma unroll
;             for (int d0 = 0; d0 < 2; ++d0) stg[orow * 64 + d0 * 32 + r32] = (bf16)f2bf(o[d0][r] * rli[r]); }
;         asm volatile("s_waitcnt lgkmcnt(0)" ::: "memory");
;         int lf = lane; asm volatile("" : "+v"(lf));
;         const size_t rowb = (size_t)(q0 + wid * 32);
; #pragma unroll
;         for (int i = 0; i < 4; ++i) { const int row = i * 8 + (lf >> 3), ch = lf & 7;
;             const v4u sv = *(const LAS v4u*)(stg + row * 64 + ch * 8);
;             const v4u gv = *(const v4u*)(C.GF + (rowb + row) * 512 + h * 64 + ch * 8);
.LBB0_806:
	s_or_b64 exec, exec, s[2:3]
	s_waitcnt lgkmcnt(0)
	s_barrier
	v_lshl_add_u32 v2, v206, 2, s0
	ds_read_b128 v[4:7], v2 offset:128
	ds_read_b128 v[8:11], v2 offset:160
	s_lshl_b32 s0, s71, 12
	s_add_i32 s0, s0, 0
	v_lshlrev_b32_e32 v54, 9, v205
	s_waitcnt lgkmcnt(1)
	v_rcp_f32_e32 v12, v4
	v_rcp_f32_e32 v13, v5
	v_rcp_f32_e32 v14, v6
	v_rcp_f32_e32 v15, v7
	s_waitcnt lgkmcnt(0)
	v_rcp_f32_e32 v16, v8
	ds_read_b128 v[4:7], v2 offset:192
	v_rcp_f32_e32 v17, v9
	v_rcp_f32_e32 v52, v10
	v_rcp_f32_e32 v53, v11
	ds_read_b128 v[8:11], v2 offset:224
	s_waitcnt lgkmcnt(1)
	v_rcp_f32_e32 v2, v4
	v_rcp_f32_e32 v4, v5
	v_rcp_f32_e32 v5, v6
	v_rcp_f32_e32 v6, v7
	s_waitcnt lgkmcnt(0)
	v_rcp_f32_e32 v7, v8
	v_rcp_f32_e32 v8, v9
	v_rcp_f32_e32 v9, v10
	v_rcp_f32_e32 v10, v11
	v_lshlrev_b32_e32 v11, 1, v204
	v_mul_f32_e32 v20, v20, v12
	v_add3_u32 v11, s0, v11, v54
	v_bfe_u32 v54, v20, 16, 1
	v_add3_u32 v20, v20, v54, s79
	v_mul_f32_e32 v12, v36, v12
	ds_write_b16_d16_hi v11, v20
	v_bfe_u32 v20, v12, 16, 1
	v_add3_u32 v12, v12, v20, s79
	ds_write_b16_d16_hi v11, v12 offset:64
	v_mul_f32_e32 v12, v21, v13
	v_bfe_u32 v20, v12, 16, 1
	v_add3_u32 v12, v12, v20, s79
	ds_write_b16_d16_hi v11, v12 offset:128
	v_mul_f32_e32 v12, v37, v13
	v_bfe_u32 v13, v12, 16, 1
	v_add3_u32 v12, v12, v13, s79
	ds_write_b16_d16_hi v11, v12 offset:192
	v_mul_f32_e32 v12, v22, v14
	v_bfe_u32 v13, v12, 16, 1
	v_add3_u32 v12, v12, v13, s79
	ds_write_b16_d16_hi v11, v12 offset:256
	v_mul_f32_e32 v12, v38, v14
	v_bfe_u32 v13, v12, 16, 1
	v_add3_u32 v12, v12, v13, s79
	ds_write_b16_d16_hi v11, v12 offset:320
	v_mul_f32_e32 v12, v23, v15
	v_bfe_u32 v13, v12, 16, 1
	v_add3_u32 v12, v12, v13, s79
	ds_write_b16_d16_hi v11, v12 offset:384
	v_mul_f32_e32 v12, v39, v15
	v_bfe_u32 v13, v12, 16, 1
	v_add3_u32 v12, v12, v13, s79
	ds_write_b16_d16_hi v11, v12 offset:448
	v_mul_f32_e32 v12, v24, v16
	v_bfe_u32 v13, v12, 16, 1
	v_add3_u32 v12, v12, v13, s79
	ds_write_b16_d16_hi v11, v12 offset:1024
	v_mul_f32_e32 v12, v40, v16
	v_bfe_u32 v13, v12, 16, 1
	v_add3_u32 v12, v12, v13, s79
	ds_write_b16_d16_hi v11, v12 offset:1088
	v_mul_f32_e32 v12, v25, v17
	v_bfe_u32 v13, v12, 16, 1
	v_add3_u32 v12, v12, v13, s79
	ds_write_b16_d16_hi v11, v12 offset:1152
	v_mul_f32_e32 v12, v41, v17
	v_bfe_u32 v13, v12, 16, 1
	v_add3_u32 v12, v12, v13, s79
	ds_write_b16_d16_hi v11, v12 offset:1216
	v_mul_f32_e32 v12, v26, v52
	v_bfe_u32 v13, v12, 16, 1
	v_add3_u32 v12, v12, v13, s79
	ds_write_b16_d16_hi v11, v12 offset:1280
	v_mul_f32_e32 v12, v42, v52
	v_bfe_u32 v13, v12, 16, 1
	v_add3_u32 v12, v12, v13, s79
	ds_write_b16_d16_hi v11, v12 offset:1344
	v_mul_f32_e32 v12, v27, v53
	v_bfe_u32 v13, v12, 16, 1
	v_add3_u32 v12, v12, v13, s79
	ds_write_b16_d16_hi v11, v12 offset:1408
	v_mul_f32_e32 v12, v43, v53
	v_bfe_u32 v13, v12, 16, 1
	v_add3_u32 v12, v12, v13, s79
	ds_write_b16_d16_hi v11, v12 offset:1472
	v_mul_f32_e32 v12, v28, v2
	v_bfe_u32 v13, v12, 16, 1
	v_add3_u32 v12, v12, v13, s79
	v_mul_f32_e32 v2, v44, v2
	ds_write_b16_d16_hi v11, v12 offset:2048
	v_bfe_u32 v12, v2, 16, 1
	v_add3_u32 v2, v2, v12, s79
	ds_write_b16_d16_hi v11, v2 offset:2112
	v_mul_f32_e32 v2, v29, v4
	v_bfe_u32 v12, v2, 16, 1
	v_add3_u32 v2, v2, v12, s79
	ds_write_b16_d16_hi v11, v2 offset:2176
	v_mul_f32_e32 v2, v45, v4
	v_bfe_u32 v4, v2, 16, 1
	v_add3_u32 v2, v2, v4, s79
	ds_write_b16_d16_hi v11, v2 offset:2240
	v_mul_f32_e32 v2, v30, v5
	v_bfe_u32 v4, v2, 16, 1
	v_add3_u32 v2, v2, v4, s79
	ds_write_b16_d16_hi v11, v2 offset:2304
	v_mul_f32_e32 v2, v46, v5
	v_bfe_u32 v4, v2, 16, 1
	v_add3_u32 v2, v2, v4, s79
	ds_write_b16_d16_hi v11, v2 offset:2368
	v_mul_f32_e32 v2, v31, v6
	v_bfe_u32 v4, v2, 16, 1
	v_add3_u32 v2, v2, v4, s79
	ds_write_b16_d16_hi v11, v2 offset:2432
	v_mul_f32_e32 v2, v47, v6
	v_bfe_u32 v4, v2, 16, 1
	v_add3_u32 v2, v2, v4, s79
	ds_write_b16_d16_hi v11, v2 offset:2496
	v_mul_f32_e32 v2, v32, v7
	v_bfe_u32 v4, v2, 16, 1
	v_add3_u32 v2, v2, v4, s79
	ds_write_b16_d16_hi v11, v2 offset:3072
	v_mul_f32_e32 v2, v48, v7
	v_bfe_u32 v4, v2, 16, 1
	v_add3_u32 v2, v2, v4, s79
	ds_write_b16_d16_hi v11, v2 offset:3136
	v_mul_f32_e32 v2, v33, v8
	v_bfe_u32 v4, v2, 16, 1
	v_add3_u32 v2, v2, v4, s79
	ds_write_b16_d16_hi v11, v2 offset:3200
	v_mul_f32_e32 v2, v49, v8
	v_bfe_u32 v4, v2, 16, 1
	v_add3_u32 v2, v2, v4, s79
	ds_write_b16_d16_hi v11, v2 offset:3264
	v_mul_f32_e32 v2, v34, v9
	v_bfe_u32 v4, v2, 16, 1
	v_add3_u32 v2, v2, v4, s79
	ds_write_b16_d16_hi v11, v2 offset:3328
	v_mul_f32_e32 v2, v50, v9
	v_bfe_u32 v4, v2, 16, 1
	v_add3_u32 v2, v2, v4, s79
	ds_write_b16_d16_hi v11, v2 offset:3392
	v_mul_f32_e32 v2, v35, v10
	v_bfe_u32 v4, v2, 16, 1
	v_add3_u32 v2, v2, v4, s79
	ds_write_b16_d16_hi v11, v2 offset:3456
	v_mul_f32_e32 v2, v51, v10
	v_bfe_u32 v4, v2, 16, 1
	v_add3_u32 v2, v2, v4, s79
	ds_write_b16_d16_hi v11, v2 offset:3520
	s_waitcnt lgkmcnt(0)
	v_readlane_b32 s2, v253, 52
	v_ashrrev_i32_e32 v12, 3, v19
	v_ashrrev_i32_e32 v13, 31, v12
	v_lshl_add_u64 v[14:15], v[12:13], 0, s[72:73]
	v_lshlrev_b64 v[4:5], 10, v[14:15]
	v_readlane_b32 s3, v253, 53
	v_lshlrev_b32_e32 v2, 4, v19
	s_mov_b32 s71, s77
	v_lshl_add_u64 v[4:5], s[2:3], 0, v[4:5]
	v_and_b32_e32 v2, 0x70, v2
	v_lshl_add_u64 v[4:5], v[4:5], 0, s[70:71]
	v_lshl_add_u64 v[4:5], v[4:5], 0, v[2:3]
	global_load_dwordx4 v[4:7], v[4:5], off
	v_add_u32_e32 v19, s0, v2
	v_lshl_add_u32 v8, v12, 7, v19
	ds_read_b128 v[8:11], v8
	v_readlane_b32 s0, v253, 28
	v_readlane_b32 s1, v253, 29
	s_waitcnt lgkmcnt(0)
	v_lshlrev_b32_e32 v16, 16, v8
	v_and_b32_e32 v17, 0xffff0000, v8
	v_lshlrev_b32_e32 v8, 16, v9
	v_and_b32_e32 v9, 0xffff0000, v9
	s_waitcnt vmcnt(0)
; #define LAS __attribute__((address_space(3)))
; __device__ __forceinline__ unsigned pk2(float lo, float hi) { f32x2_t v = {lo, hi}; bf16x2_t b = __builtin_convertvector(v, bf16x2_t); return __builtin_bit_cast(unsigned, b); }
; template <bool NOMAX>
; __device__ __forceinline__ void fox_unit(const AttnCtx& C, int u, LAS unsigned char* lds) {
;     ...
;         for (int i = 0; i < 4; ++i) { const int row = i * 8 + (lf >> 3), ch = lf & 7;
;             const v4u sv = *(const LAS v4u*)(stg + row * 64 + ch * 8);
;             const v4u gv = *(const v4u*)(C.GF + (rowb + row) * 512 + h * 64 + ch * 8);
;             v4u ov;
;             ov.x = pk2(__builtin_bit_cast(float, sv.x << 16) * __builtin_bit_cast(float, gv.x << 16), __builtin_bit_cast(float, sv.x & 0xffff0000u) * __builtin_bit_cast(float, gv.x & 0xffff0000u));
;             ov.y = pk2(__builtin_bit_cast(float, sv.y << 16) * __builtin_bit_cast(float, gv.y << 16), __builtin_bit_cast(float, sv.y & 0xffff0000u) * __builtin_bit_cast(float, gv.y & 0xffff0000u));
;             ov.z = pk2(__builtin_bit_cast(float, sv.z << 16) * __builtin_bit_cast(float, gv.z << 16), __builtin_bit_cast(float, sv.z & 0xffff0000u) * __builtin_bit_cast(float, gv.z & 0xffff0000u));
;             ov.w = pk2(__builtin_bit_cast(float, sv.w << 16) * __builtin_bit_cast(float, gv.w << 16), __builtin_bit_cast(float, sv.w & 0xffff0000u) * __builtin_bit_cast(float, gv.w & 0xffff0000u));
;             *(v4u*)(C.MIX + (rowb + row) * 1024 + h * 64 + ch * 8) = ov; }
;     }
;     asm volatile("s_waitcnt vmcnt(0) lgkmcnt(0)\n\ts_barrier" ::: "memory");
; template <int KIND>
; __device__ __forceinline__ void attn_queue(const AttnCtx& C, unsigned* head, int nunits, LAS unsigned char* lds) {
;     ...
;         __syncthreads();
;         if (threadIdx.x == 0) slot[0] = __hip_atomic_fetch_add(head, 1u, __ATOMIC_RELAXED, __HIP_MEMORY_SCOPE_AGENT);
	v_lshlrev_b32_e32 v20, 16, v4
	v_and_b32_e32 v21, 0xffff0000, v4
	v_pk_mul_f32 v[16:17], v[16:17], v[20:21]
	s_nop 0
	v_cvt_pk_bf16_f32 v4, v16, v17
	v_lshlrev_b32_e32 v16, 16, v5
	v_and_b32_e32 v17, 0xffff0000, v5
	v_pk_mul_f32 v[8:9], v[8:9], v[16:17]
	v_lshlrev_b32_e32 v16, 16, v6
	v_cvt_pk_bf16_f32 v5, v8, v9
	v_lshlrev_b32_e32 v8, 16, v10
	v_and_b32_e32 v9, 0xffff0000, v10
	v_and_b32_e32 v17, 0xffff0000, v6
	v_pk_mul_f32 v[8:9], v[8:9], v[16:17]
	v_lshlrev_b32_e32 v10, 16, v7
	v_cvt_pk_bf16_f32 v6, v8, v9
	v_lshlrev_b32_e32 v8, 16, v11
	v_and_b32_e32 v9, 0xffff0000, v11
	v_and_b32_e32 v11, 0xffff0000, v7
	v_pk_mul_f32 v[8:9], v[8:9], v[10:11]
	s_nop 0
	v_cvt_pk_bf16_f32 v7, v8, v9
	v_lshlrev_b64 v[8:9], 11, v[14:15]
	v_lshl_add_u64 v[8:9], s[0:1], 0, v[8:9]
	v_lshl_add_u64 v[8:9], v[8:9], 0, s[70:71]
	v_lshl_add_u64 v[8:9], v[8:9], 0, v[2:3]
	global_store_dwordx4 v[8:9], v[4:7], off
	v_add_u32_e32 v8, 8, v12
	v_ashrrev_i32_e32 v9, 31, v8
	v_lshl_add_u64 v[14:15], v[8:9], 0, s[72:73]
	v_lshlrev_b64 v[4:5], 10, v[14:15]
	v_lshl_add_u64 v[4:5], s[2:3], 0, v[4:5]
	v_lshl_add_u64 v[4:5], v[4:5], 0, s[70:71]
	v_lshl_add_u64 v[4:5], v[4:5], 0, v[2:3]
	global_load_dwordx4 v[4:7], v[4:5], off
	v_lshl_add_u32 v8, v8, 7, v19
	ds_read_b128 v[8:11], v8
	s_waitcnt lgkmcnt(0)
	v_lshlrev_b32_e32 v16, 16, v8
	v_and_b32_e32 v17, 0xffff0000, v8
	v_lshlrev_b32_e32 v8, 16, v9
	v_and_b32_e32 v9, 0xffff0000, v9
	s_waitcnt vmcnt(0)
	v_lshlrev_b32_e32 v20, 16, v4
	v_and_b32_e32 v21, 0xffff0000, v4
	v_pk_mul_f32 v[16:17], v[16:17], v[20:21]
	s_nop 0
	v_cvt_pk_bf16_f32 v4, v16, v17
	v_lshlrev_b32_e32 v16, 16, v5
	v_and_b32_e32 v17, 0xffff0000, v5
	v_pk_mul_f32 v[8:9], v[8:9], v[16:17]
	v_lshlrev_b32_e32 v16, 16, v6
	v_cvt_pk_bf16_f32 v5, v8, v9
	v_lshlrev_b32_e32 v8, 16, v10
	v_and_b32_e32 v9, 0xffff0000, v10
	v_and_b32_e32 v17, 0xffff0000, v6
	v_pk_mul_f32 v[8:9], v[8:9], v[16:17]
	v_lshlrev_b32_e32 v10, 16, v7
	v_cvt_pk_bf16_f32 v6, v8, v9
	v_lshlrev_b32_e32 v8, 16, v11
	v_and_b32_e32 v9, 0xffff0000, v11
	v_and_b32_e32 v11, 0xffff0000, v7
	v_pk_mul_f32 v[8:9], v[8:9], v[10:11]
	s_nop 0
	v_cvt_pk_bf16_f32 v7, v8, v9
	v_lshlrev_b64 v[8:9], 11, v[14:15]
	v_lshl_add_u64 v[8:9], s[0:1], 0, v[8:9]
	v_lshl_add_u64 v[8:9], v[8:9], 0, s[70:71]
	v_lshl_add_u64 v[8:9], v[8:9], 0, v[2:3]
	global_store_dwordx4 v[8:9], v[4:7], off
	v_add_u32_e32 v8, 16, v12
	v_ashrrev_i32_e32 v9, 31, v8
	v_lshl_add_u64 v[14:15], v[8:9], 0, s[72:73]
	v_lshlrev_b64 v[4:5], 10, v[14:15]
	v_lshl_add_u64 v[4:5], s[2:3], 0, v[4:5]
	v_lshl_add_u64 v[4:5], v[4:5], 0, s[70:71]
	v_lshl_add_u64 v[4:5], v[4:5], 0, v[2:3]
	global_load_dwordx4 v[4:7], v[4:5], off
	v_lshl_add_u32 v8, v8, 7, v19
	ds_read_b128 v[8:11], v8
	s_waitcnt lgkmcnt(0)
	v_lshlrev_b32_e32 v16, 16, v8
	v_and_b32_e32 v17, 0xffff0000, v8
	v_lshlrev_b32_e32 v8, 16, v9
	v_and_b32_e32 v9, 0xffff0000, v9
	v_lshlrev_b32_e32 v20, 16, v10
	v_and_b32_e32 v21, 0xffff0000, v10
	v_lshlrev_b32_e32 v10, 16, v11
	v_and_b32_e32 v11, 0xffff0000, v11
	s_waitcnt vmcnt(0)
	v_lshlrev_b32_e32 v22, 16, v4
	v_and_b32_e32 v23, 0xffff0000, v4
	v_lshlrev_b32_e32 v4, 16, v5
	v_and_b32_e32 v5, 0xffff0000, v5
	v_pk_mul_f32 v[8:9], v[8:9], v[4:5]
	v_lshlrev_b32_e32 v24, 16, v6
	v_cvt_pk_bf16_f32 v5, v8, v9
	v_lshlrev_b64 v[8:9], 11, v[14:15]
	v_and_b32_e32 v25, 0xffff0000, v6
	v_lshlrev_b32_e32 v6, 16, v7
	v_and_b32_e32 v7, 0xffff0000, v7
	v_lshl_add_u64 v[8:9], s[0:1], 0, v[8:9]
	v_pk_mul_f32 v[16:17], v[16:17], v[22:23]
	v_pk_mul_f32 v[20:21], v[20:21], v[24:25]
	v_pk_mul_f32 v[10:11], v[10:11], v[6:7]
	v_lshl_add_u64 v[8:9], v[8:9], 0, s[70:71]
	v_cvt_pk_bf16_f32 v4, v16, v17
	v_cvt_pk_bf16_f32 v6, v20, v21
	v_cvt_pk_bf16_f32 v7, v10, v11
	v_lshl_add_u64 v[8:9], v[8:9], 0, v[2:3]
	global_store_dwordx4 v[8:9], v[4:7], off
	v_add_u32_e32 v8, 24, v12
	v_ashrrev_i32_e32 v9, 31, v8
	v_lshl_add_u64 v[12:13], v[8:9], 0, s[72:73]
	v_lshlrev_b64 v[4:5], 10, v[12:13]
	v_lshl_add_u64 v[4:5], s[2:3], 0, v[4:5]
	v_lshl_add_u64 v[4:5], v[4:5], 0, s[70:71]
	v_lshl_add_u64 v[4:5], v[4:5], 0, v[2:3]
	global_load_dwordx4 v[4:7], v[4:5], off
	v_lshl_add_u32 v8, v8, 7, v19
	ds_read_b128 v[8:11], v8
	v_lshlrev_b64 v[12:13], 11, v[12:13]
	v_lshl_add_u64 v[12:13], s[0:1], 0, v[12:13]
	v_lshl_add_u64 v[12:13], v[12:13], 0, s[70:71]
	s_waitcnt lgkmcnt(0)
	v_lshlrev_b32_e32 v14, 16, v8
	v_and_b32_e32 v15, 0xffff0000, v8
	v_lshlrev_b32_e32 v8, 16, v9
	v_and_b32_e32 v9, 0xffff0000, v9
	v_lshlrev_b32_e32 v16, 16, v10
	v_and_b32_e32 v17, 0xffff0000, v10
	v_lshlrev_b32_e32 v10, 16, v11
	v_and_b32_e32 v11, 0xffff0000, v11
	s_waitcnt vmcnt(0)
	v_lshlrev_b32_e32 v20, 16, v4
	v_and_b32_e32 v21, 0xffff0000, v4
	v_lshlrev_b32_e32 v4, 16, v5
	v_and_b32_e32 v5, 0xffff0000, v5
	v_lshlrev_b32_e32 v22, 16, v6
	v_and_b32_e32 v23, 0xffff0000, v6
	v_lshlrev_b32_e32 v6, 16, v7
	v_and_b32_e32 v7, 0xffff0000, v7
	v_pk_mul_f32 v[14:15], v[14:15], v[20:21]
	v_pk_mul_f32 v[8:9], v[8:9], v[4:5]
	v_pk_mul_f32 v[16:17], v[16:17], v[22:23]
	v_pk_mul_f32 v[10:11], v[10:11], v[6:7]
	v_cvt_pk_bf16_f32 v4, v14, v15
	v_cvt_pk_bf16_f32 v5, v8, v9
	v_cvt_pk_bf16_f32 v6, v16, v17
	v_cvt_pk_bf16_f32 v7, v10, v11
	v_lshl_add_u64 v[8:9], v[12:13], 0, v[2:3]
	global_store_dwordx4 v[8:9], v[4:7], off
	s_mov_b64 s[98:99], exec
	v_readlane_b32 s0, v253, 26
	v_readlane_b32 s1, v253, 27
	s_and_b64 s[0:1], s[98:99], s[0:1]
	s_mov_b64 exec, s[0:1]
	s_cbranch_execz .Lpp_f_skipa
	v_readlane_b32 s94, v252, 16
	v_readlane_b32 s95, v252, 17
	v_mov_b32_e32 v254, 0
	v_mov_b32_e32 v4, 1
	s_nop 4
	global_atomic_add v4, v254, v4, s[94:95] offset:1024 sc0
.Lpp_f_skipa:
	s_mov_b64 exec, s[98:99]
	s_mov_b32 s101, 1
	s_waitcnt vmcnt(0) lgkmcnt(0)
	s_barrier

; template <int KIND>
; __device__ __forceinline__ void attn_queue(const AttnCtx& C, unsigned* head, int nunits, LAS unsigned char* lds) {
;     ...
;         __syncthreads();
;         if (threadIdx.x == 0) slot[0] = __hip_atomic_fetch_add(head, 1u, __ATOMIC_RELAXED, __HIP_MEMORY_SCOPE_AGENT);
.LBB0_809:
	s_barrier
	s_mov_b64 s[2:3], exec
	v_readlane_b32 s0, v253, 26
	v_readlane_b32 s1, v253, 27
	s_and_b64 s[0:1], s[2:3], s[0:1]
	s_mov_b64 exec, s[0:1]
	s_cbranch_execz .LBB0_813
	s_mov_b64 s[6:7], exec
	v_mbcnt_lo_u32_b32 v2, s6, 0
	v_mbcnt_hi_u32_b32 v2, s7, v2
	v_cmp_eq_u32_e32 vcc, 0, v2
	s_and_saveexec_b64 s[4:5], vcc
	s_cbranch_execz .LBB0_812
	s_cmp_eq_u32 s101, 1
	s_cbranch_scc1 .LBB0_812
	s_bcnt1_i32_b64 s0, s[6:7]
	v_mov_b32_e32 v4, s0
	global_atomic_add v4, v3, v4, s[94:95] offset:1024 sc0

; template <bool NOMAX>
; __device__ __forceinline__ void fox_unit(const AttnCtx& C, int u, LAS unsigned char* lds) {
;     ...
;     const int h = u & 7, qb = 63 - (u >> 3);
;     const int NT = 4 * qb + 4, tref = 4 * qb, q0 = 256 * qb;
;     LAS float* ckl = (LAS float*)(lds + TF_CK);
;     LAS float* wsf = (LAS float*)(lds + TF_WS) + wid * 64;
;     const LAS float* PREh = (const LAS float*)(lds + FX_PRE) + h * FX_PST; const LAS float* NRMF = (const LAS float*)(lds + FX_NRM);
;     __syncthreads();
;     const bf16* Qw = C.QF + (size_t)(q0 + wid * 32) * 512 + h * 64;
;     const bf16* Kh = C.KF + h * 64; const bf16* Vh = C.VF + h * 64;
;     const unsigned lds0 = (unsigned)(size_t)lds;
;     const bf16* ksrc = Kh + (size_t)lane * 512 + wid * 8;
;     const bf16* vsrc = Vh + (size_t)(16 * (wid & 3) + (lane >> 2)) * 512 + (wid >> 2) * 32 + (lane & 3) * 8;
;     const unsigned kdst = lds0 + TF_K + wid * 1024, vdst = lds0 + TF_V + wid * 1024;
;     ...
;     const lcp kp0 = (lcp)(lds + TF_K) + hi * 1024 + r32 * 16;
;     const lcp vp0 = (lcp)(lds + TF_V) + ((lane >> 4) & 1) * 32 + (lane & 3) * 8 + (4 * hi + ((lane & 15) >> 2)) * 64;
;     DMA_K(tref, 0); DMA_K(tref + 1, SLOTB); DMA_K(tref + 2, 2 * SLOTB); DMA_K(tref + 3, 3 * SLOTB);
;     bf16x8 qr[4];
; template <int KIND>
; __device__ __forceinline__ void attn_queue(const AttnCtx& C, unsigned* head, int nunits, LAS unsigned char* lds) {
;     ...
;         const unsigned u = slot[0];
;         if (u >= (unsigned)nunits) break;
;         if (KIND == 0) {
;             bool nmx_ = false;
;             if constexpr (KIND == 0) { const int hh_ = (int)u & 7, tr_ = 4 * (63 - ((int)u >> 3)); const LAS float* pr_ = (const LAS float*)(lds + tuned::FX_PRE) + hh_ * tuned::FX_PST; const LAS float* nr_ = (const LAS float*)(lds + tuned::FX_NRM);
;                 const float g_ = (pr_[tr_] - pr_[tr_ + 4]) * LOG2E, b_ = 1.01f * sqrtf((nr_[hh_ * 2] + nr_[hh_ * 2 + 1]) * (nr_[16 + hh_ * 2] + nr_[16 + hh_ * 2 + 1]));
;                 nmx_ = __builtin_amdgcn_readfirstlane((b_ + g_ <= 100.0f) ? 1 : 0) != 0; }
;             if (nmx_) tuned::fox_unit<true>(C, (int)u, lds); else tuned::fox_unit<false>(C, (int)u, lds); } else if (KIND == 1) { if ((C.nomax >> (2 * ((int)u & 3) + (((int)u >> 2) & 1))) & 1) tuned::diff_unit<true>(C, (int)u, lds); else tuned::diff_unit<false>(C, (int)u, lds); } else { if constexpr (KIND == 3) { sample_diff2<0>(C, (int)u, lds);
.LBB0_813:
	s_or_b64 exec, exec, s[2:3]
	s_mov_b32 s101, 0
	s_waitcnt lgkmcnt(0)
	s_barrier
	ds_read_b32 v2, v1
	s_movk_i32 s0, 0x1ff
	s_mov_b64 s[2:3], -1
	s_waitcnt lgkmcnt(0)
	v_cmp_lt_u32_e32 vcc, s0, v2
	v_readfirstlane_b32 s1, v2
	s_cbranch_vccnz .LBB0_808
	s_and_b32 s86, s1, 7
	s_lshl_b32 s3, s86, 3
	s_add_i32 s3, s3, 0
	s_add_i32 s10, s3, 0x25080
	v_mov_b32_e32 v2, s10
	ds_read2_b64 v[4:7], v2 offset1:8
	s_not_b32 s2, s1
	s_mul_i32 s0, s86, 0x410
	s_add_i32 s0, s0, 0
	s_lshl_b32 s2, s2, 1
	s_add_i32 s0, s0, 0x22800
	s_and_b32 s2, s2, 0x3f0
	s_add_i32 s2, s0, s2
	s_waitcnt lgkmcnt(0)
	v_mov_b32_e32 v10, v4
	v_mov_b32_e32 v11, v6
	v_mov_b32_e32 v6, v5
	v_mov_b32_e32 v2, s2
	v_pk_add_f32 v[4:5], v[10:11], v[6:7]
	ds_read2_b32 v[8:9], v2 offset1:4
	v_mul_f32_e32 v2, v4, v5
	v_mul_f32_e32 v4, 0x4f800000, v2
	v_cmp_gt_f32_e32 vcc, s9, v2
	s_lshr_b32 s1, s1, 3
	s_xor_b32 s88, s1, 63
	v_cndmask_b32_e32 v2, v2, v4, vcc
	v_sqrt_f32_e32 v5, v2
	s_waitcnt lgkmcnt(0)
	v_sub_f32_e32 v4, v8, v9
	s_lshl_b32 s78, s88, 2
	s_lshl_b32 s11, s88, 8
	v_add_u32_e32 v6, -1, v5
	v_fma_f32 v7, -v6, v5, v2
	v_cmp_ge_f32_e64 s[2:3], 0, v7
	v_add_u32_e32 v7, 1, v5
	s_lshl_b32 s12, s86, 6
	v_cndmask_b32_e64 v6, v5, v6, s[2:3]
	v_fma_f32 v5, -v7, v5, v2
	v_cmp_lt_f32_e64 s[2:3], 0, v5
	s_lshl_b32 s1, s86, 7
	v_readlane_b32 s4, v253, 48
	v_cndmask_b32_e64 v5, v6, v7, s[2:3]
	v_mul_f32_e32 v6, 0x37800000, v5
	v_cndmask_b32_e32 v5, v5, v6, vcc
	v_cmp_class_f32_e32 vcc, v2, v211
	s_mov_b32 s2, 0x3fb8aa3b
	s_mov_b32 s3, 0x3f8147ae
	v_cndmask_b32_e32 v5, v5, v2, vcc
	v_pk_mul_f32 v[4:5], v[4:5], s[2:3]
	s_mov_b32 s2, 0x42c80000
	v_add_f32_e32 v2, v4, v5
	v_cmp_ge_f32_e32 vcc, s2, v2
	v_readlane_b32 s5, v253, 49
	s_nop 0
	v_cndmask_b32_e64 v2, 0, 1, vcc
	s_nop 0
	v_readfirstlane_b32 s2, v2
	s_and_b32 s2, s2, 1
	s_add_u32 s74, s4, s1
	s_addc_u32 s75, s5, 0
	s_cmp_eq_u32 s2, 0
	s_mov_b64 s[2:3], -1
	s_cbranch_scc0 .LBB0_949
	v_mov_b32_e32 v8, v0
	v_readlane_b32 s4, v253, 30
	v_readfirstlane_b32 s1, v8
	s_ashr_i32 s87, s1, 6
	s_lshl_b32 s8, s87, 5
	s_add_i32 s84, s8, s11
	s_ashr_i32 s85, s84, 31
	s_lshl_b64 s[2:3], s[84:85], 10
	v_readlane_b32 s5, v253, 31
	s_add_u32 s2, s4, s2
	s_addc_u32 s3, s5, s3
	s_lshl_b32 s72, s12, 1
	v_and_b32_e32 v212, 63, v8
	s_add_u32 s2, s2, s72
	s_addc_u32 s3, s3, 0
	v_lshlrev_b32_e32 v2, 10, v212
	s_lshl_b32 s4, s87, 3
	v_lshl_add_u64 v[4:5], s[74:75], 0, v[2:3]
	s_ashr_i32 s5, s4, 31
	v_lshl_add_u64 v[206:207], s[4:5], 1, v[4:5]
	s_lshl_b32 s92, s87, 10
	s_lshl_b32 s76, s88, 18
	s_barrier
	s_add_i32 s92, s92, 0
	v_lshl_add_u64 v[4:5], v[206:207], 0, s[76:77]
	s_mov_b32 s4, m0
	s_mov_b32 m0, s92
	s_nop 0
	global_load_lds_dwordx4 v[4:5], off
	s_mov_b32 m0, s4
	s_mov_b64 s[4:5], 0x10000
	v_lshl_add_u64 v[6:7], v[4:5], 0, s[4:5]
	s_add_i32 s82, s92, 0x2000
	s_mov_b32 s4, m0
	s_mov_b32 m0, s82
	s_nop 0
	global_load_lds_dwordx4 v[6:7], off
	s_mov_b32 m0, s4
	s_mov_b64 s[4:5], 0x20000
	v_lshl_add_u64 v[6:7], v[4:5], 0, s[4:5]
	s_add_i32 s83, s92, 0x4000
	s_mov_b32 s4, m0
	s_mov_b32 m0, s83
	s_nop 0
	global_load_lds_dwordx4 v[6:7], off
	s_mov_b32 m0, s4
	v_and_b32_e32 v213, 31, v8
	s_mov_b64 s[4:5], 0x30000
	v_bfe_u32 v214, v8, 5, 1
	v_lshl_add_u64 v[4:5], v[4:5], 0, s[4:5]
	v_lshlrev_b32_e32 v2, 10, v213
	s_add_i32 s93, s92, 0x6000
	s_mov_b32 s4, m0
	s_mov_b32 m0, s93
	s_nop 0
	global_load_lds_dwordx4 v[4:5], off
	s_mov_b32 m0, s4
	v_lshl_add_u64 v[6:7], s[2:3], 0, v[2:3]
	v_lshlrev_b32_e32 v4, 4, v214
	v_mov_b32_e32 v5, v3
	v_lshl_add_u64 v[6:7], v[6:7], 0, v[4:5]
	global_load_dwordx4 v[142:145], v[6:7], off
	global_load_dwordx4 v[138:141], v[6:7], off offset:32
	global_load_dwordx4 v[134:137], v[6:7], off offset:64
	global_load_dwordx4 v[130:133], v[6:7], off offset:96
	v_mov_b32_e32 v2, s10
	ds_read2_b64 v[10:13], v2 offset1:8
	s_lshl_b32 s2, s78, 2
	s_add_i32 s2, s0, s2
	v_mov_b32_e32 v6, s2
	s_lshl_b32 s76, s86, 2
	s_waitcnt lgkmcnt(0)
	v_add_f32_e32 v2, v10, v11
	v_add_f32_e32 v5, v12, v13
	v_mul_f32_e32 v2, v2, v5
	v_mul_f32_e32 v5, 0x4f800000, v2
	v_cmp_gt_f32_e32 vcc, s9, v2
	s_nop 1
	v_cndmask_b32_e32 v2, v2, v5, vcc
	v_sqrt_f32_e32 v5, v2
	s_nop 0
	v_add_u32_e32 v7, -1, v5
	v_fma_f32 v9, -v7, v5, v2
	v_cmp_ge_f32_e64 s[2:3], 0, v9
	v_add_u32_e32 v9, 1, v5
	s_nop 0
	v_cndmask_b32_e64 v7, v5, v7, s[2:3]
	v_fma_f32 v5, -v9, v5, v2
	v_cmp_lt_f32_e64 s[2:3], 0, v5
	s_nop 1
	v_cndmask_b32_e64 v5, v7, v9, s[2:3]
	s_lshl_b32 s2, s88, 5
	v_mul_f32_e32 v7, 0x37800000, v5
	s_add_i32 s2, s2, 0
	v_cndmask_b32_e32 v5, v5, v7, vcc
	v_cmp_class_f32_e32 vcc, v2, v211
	s_add_i32 s2, s2, s76
	s_add_i32 s2, s2, 0x24880
	v_cndmask_b32_e32 v2, v5, v2, vcc
	v_mul_f32_e32 v10, 0x3f8147ae, v2
	v_mov_b32_e32 v5, s2
	ds_read_b32 v2, v6
	ds_read_b32 v7, v5
	s_cmp_lt_u32 s1, 64
	v_lshlrev_b32_e32 v9, 2, v212
	s_cselect_b64 s[70:71], -1, 0
	s_cmp_gt_u32 s1, 63
	v_cmp_gt_u32_e32 vcc, s78, v9
	s_cbranch_scc1 .LBB0_835
	v_fmaak_f32 v5, 2.0, v10, 0x42400000
	v_mul_f32_e32 v6, 0xbf317218, v5
	v_mov_b32_e32 v5, 0
	s_and_saveexec_b64 s[2:3], vcc
	s_cbranch_execz .LBB0_820
	v_sub_u32_e32 v5, s78, v9
	v_lshl_add_u32 v5, v5, 2, s0
	ds_read_b32 v5, v5
	s_waitcnt lgkmcnt(0)
	v_sub_f32_e32 v5, v5, v2
	v_sub_f32_e32 v5, v7, v5
	v_cmp_le_f32_e32 vcc, v5, v6
	v_mov_b32_e32 v5, 0
	s_and_saveexec_b64 s[4:5], vcc
	v_mov_b32_e32 v5, 1
	s_or_b64 exec, exec, s[4:5]

; #define LAS __attribute__((address_space(3)))
; __device__ __forceinline__ unsigned f2bf(float f) { unsigned u = __builtin_bit_cast(unsigned, f); return (u + 0x7fffu + ((u >> 16) & 1u)) >> 16; }
; __device__ __forceinline__ int crow(int r, int hi) { return (r & 3) + 8 * (r >> 2) + 4 * hi; }
; #define TSBAR() __builtin_amdgcn_sched_barrier(0)
; #define PKW(P, B) pk2(P[B], P[B + 1])
; #define PKW(P, B) pk2(P[B], P[B + 1])
; #define PKW(P, B) pk2(P[B], P[B + 1])
; template <bool NOMAX>
; __device__ __forceinline__ void fox_unit(const AttnCtx& C, int u, LAS unsigned char* lds) {
;     ...
;     { float sacc = pB0[0] + pB0[1];
; #pragma unroll
;       for (int r = 2; r < 16; ++r) sacc += pB0[r];
; #pragma unroll
;       for (int r = 0; r < 16; ++r) sacc += pB1[r];
;       l_reg += sacc;
;       pw0 = (v4u){PKW(pB0, 0), PKW(pB0, 2), PKW(pB0, 4), PKW(pB0, 6)}; pw1 = (v4u){PKW(pB0, 8), PKW(pB0, 10), PKW(pB0, 12), PKW(pB0, 14)};
;       pw2 = (v4u){PKW(pB1, 0), PKW(pB1, 2), PKW(pB1, 4), PKW(pB1, 6)}; pw3 = (v4u){PKW(pB1, 8), PKW(pB1, 10), PKW(pB1, 12), PKW(pB1, 14)};
;       TSBAR();
;       const lcp vp_ = vp0 + sl_cur;
; #pragma unroll
;       for (int d0 = 0; d0 < 2; ++d0) {
;           const bf16x8 f0 = vfrag(vp_ + d0 * 4096), f1 = vfrag(vp_ + d0 * 4096 + 1024), f2 = vfrag(vp_ + d0 * 4096 + 2048), f3 = vfrag(vp_ + d0 * 4096 + 3072);
;           o[d0] = __builtin_amdgcn_mfma_f32_32x32x16_bf16(PAF(0), f0, o[d0], 0, 0, 0); o[d0] = __builtin_amdgcn_mfma_f32_32x32x16_bf16(PAF(1), f1, o[d0], 0, 0, 0);
;           o[d0] = __builtin_amdgcn_mfma_f32_32x32x16_bf16(PAF(2), f2, o[d0], 0, 0, 0); o[d0] = __builtin_amdgcn_mfma_f32_32x32x16_bf16(PAF(3), f3, o[d0], 0, 0, 0);
;       }
;     }
;     { auto rr = __builtin_amdgcn_permlane32_swap(__float_as_uint(l_reg), __float_as_uint(l_reg), false, false); l_reg = __uint_as_float(rr[0]) + __uint_as_float(rr[1]); }
;     if (hi == 0) wsf[32 + r32] = l_reg;
;     asm volatile("s_waitcnt lgkmcnt(0)\n\ts_barrier" ::: "memory");
;     float rli[16];
; #pragma unroll
;     for (int r = 0; r < 16; ++r) rli[r] = __builtin_amdgcn_rcpf(wsf[32 + crow(r, hi)]);
;     {
;         LAS bf16* stg = (LAS bf16*)(lds + TF_OST) + wid * 2048;
; #pragma unroll
;         for (int r = 0; r < 16; ++r) { const int orow = crow(r, hi);
; #pragma unroll
;             for (int d0 = 0; d0 < 2; ++d0) stg[orow * 64 + d0 * 32 + r32] = (bf16)f2bf(o[d0][r] * rli[r]); }
.LBB0_946:
	v_add_f32_e32 v4, v98, v99
	v_add_f32_e32 v4, v100, v4
	v_add_f32_e32 v4, v101, v4
	v_add_f32_e32 v4, v102, v4
	v_add_f32_e32 v4, v103, v4
	v_add_f32_e32 v4, v104, v4
	v_add_f32_e32 v4, v105, v4
	v_add_f32_e32 v4, v106, v4
	v_add_f32_e32 v4, v107, v4
	v_add_f32_e32 v4, v108, v4
	v_add_f32_e32 v4, v109, v4
	v_add_f32_e32 v4, v110, v4
	v_add_f32_e32 v4, v111, v4
	v_add_f32_e32 v4, v112, v4
	v_add_f32_e32 v4, v113, v4
	v_add_f32_e32 v4, v114, v4
	v_add_f32_e32 v4, v115, v4
	v_add_f32_e32 v4, v116, v4
	v_add_f32_e32 v4, v117, v4
	v_add_f32_e32 v4, v118, v4
	v_add_f32_e32 v4, v119, v4
	v_add_f32_e32 v4, v120, v4
	v_add_f32_e32 v4, v121, v4
	v_add_f32_e32 v4, v122, v4
	v_add_f32_e32 v4, v123, v4
	v_add_f32_e32 v4, v124, v4
	v_add_f32_e32 v4, v125, v4
	v_add_f32_e32 v4, v126, v4
	v_add_f32_e32 v4, v127, v4
	v_add_f32_e32 v4, v128, v4
	v_add_f32_e32 v16, v129, v4
	v_cvt_pk_bf16_f32 v4, v98, v99
	v_cvt_pk_bf16_f32 v5, v100, v101
	v_cvt_pk_bf16_f32 v6, v102, v103
	v_cvt_pk_bf16_f32 v7, v104, v105
	v_cvt_pk_bf16_f32 v8, v106, v107
	v_cvt_pk_bf16_f32 v9, v108, v109
	v_cvt_pk_bf16_f32 v10, v110, v111
	v_cvt_pk_bf16_f32 v11, v112, v113
	v_cvt_pk_bf16_f32 v12, v114, v115
	v_cvt_pk_bf16_f32 v13, v116, v117
	v_cvt_pk_bf16_f32 v14, v118, v119
	v_cvt_pk_bf16_f32 v15, v120, v121
	v_cvt_pk_bf16_f32 v20, v122, v123
	v_cvt_pk_bf16_f32 v21, v124, v125
	v_cvt_pk_bf16_f32 v22, v126, v127
	v_cvt_pk_bf16_f32 v23, v128, v129
	v_add_u32_e32 v17, s89, v218
	ds_read_b64_tr_b16 v[24:25], v17 offset:24576
	ds_read_b64_tr_b16 v[26:27], v17 offset:25088
	ds_read_b64_tr_b16 v[28:29], v17 offset:25600
	ds_read_b64_tr_b16 v[30:31], v17 offset:26112
	v_add_f32_e32 v2, v2, v16
	v_cmp_gt_u32_e32 vcc, 32, v212
	s_waitcnt lgkmcnt(2)
	v_mfma_f32_32x32x16_bf16 v[50:65], v[4:7], v[24:27], v[50:65]
	s_waitcnt lgkmcnt(0)
	v_mfma_f32_32x32x16_bf16 v[50:65], v[8:11], v[28:31], v[50:65]
	ds_read_b64_tr_b16 v[24:25], v17 offset:26624
	ds_read_b64_tr_b16 v[26:27], v17 offset:27136
	ds_read_b64_tr_b16 v[28:29], v17 offset:27648
	ds_read_b64_tr_b16 v[30:31], v17 offset:28160
	s_waitcnt lgkmcnt(2)
	v_mfma_f32_32x32x16_bf16 v[50:65], v[12:15], v[24:27], v[50:65]
	s_waitcnt lgkmcnt(0)
	v_mfma_f32_32x32x16_bf16 v[50:65], v[20:23], v[28:31], v[50:65]
	ds_read_b64_tr_b16 v[24:25], v17 offset:28672
	ds_read_b64_tr_b16 v[26:27], v17 offset:29184
	ds_read_b64_tr_b16 v[28:29], v17 offset:29696
	ds_read_b64_tr_b16 v[30:31], v17 offset:30208
	s_waitcnt lgkmcnt(2)
	v_mfma_f32_32x32x16_bf16 v[34:49], v[4:7], v[24:27], v[34:49]
	s_waitcnt lgkmcnt(0)
	v_mfma_f32_32x32x16_bf16 v[34:49], v[8:11], v[28:31], v[34:49]
	ds_read_b64_tr_b16 v[4:5], v17 offset:30720
	ds_read_b64_tr_b16 v[6:7], v17 offset:31232
	ds_read_b64_tr_b16 v[8:9], v17 offset:31744
	ds_read_b64_tr_b16 v[10:11], v17 offset:32256
	s_waitcnt lgkmcnt(2)
	v_mfma_f32_32x32x16_bf16 v[34:49], v[12:15], v[4:7], v[34:49]
	v_mov_b32_e32 v4, v2
	s_nop 1
	v_permlane32_swap_b32_e32 v2, v4
	s_waitcnt lgkmcnt(0)
	v_mfma_f32_32x32x16_bf16 v[34:49], v[20:23], v[8:11], v[34:49]
	s_and_saveexec_b64 s[2:3], vcc
	v_add_f32_e32 v2, v2, v4
	ds_write_b32 v220, v2 offset:128
	s_or_b64 exec, exec, s[2:3]
	s_waitcnt lgkmcnt(0)
	s_barrier
	ds_read_b128 v[4:7], v219 offset:128
	ds_read_b128 v[8:11], v219 offset:160
	s_lshl_b32 s1, s87, 12
	s_add_i32 s1, s1, 0
	v_lshlrev_b32_e32 v20, 1, v213
	s_waitcnt lgkmcnt(1)
	v_rcp_f32_e32 v2, v4
	v_lshlrev_b32_e32 v21, 9, v214
	v_add3_u32 v20, s1, v20, v21
	v_rcp_f32_e32 v12, v5
	v_mul_f32_e32 v21, v50, v2
	v_bfe_u32 v22, v21, 16, 1
	v_add3_u32 v21, v21, v22, s79
	v_mul_f32_e32 v2, v34, v2
	ds_write_b16_d16_hi v20, v21
	v_bfe_u32 v21, v2, 16, 1
	v_add3_u32 v2, v2, v21, s79
	ds_write_b16_d16_hi v20, v2 offset:64
	v_mul_f32_e32 v2, v51, v12
	v_bfe_u32 v21, v2, 16, 1
	v_rcp_f32_e32 v13, v6
	v_add3_u32 v2, v2, v21, s79
	ds_write_b16_d16_hi v20, v2 offset:128
	v_mul_f32_e32 v2, v35, v12
	v_bfe_u32 v12, v2, 16, 1
	v_add3_u32 v2, v2, v12, s79
	ds_write_b16_d16_hi v20, v2 offset:192
	v_mul_f32_e32 v2, v52, v13
	v_bfe_u32 v12, v2, 16, 1
	v_rcp_f32_e32 v14, v7
	v_add3_u32 v2, v2, v12, s79
	ds_write_b16_d16_hi v20, v2 offset:256
	v_mul_f32_e32 v2, v36, v13
	v_bfe_u32 v12, v2, 16, 1
	v_add3_u32 v2, v2, v12, s79
	ds_write_b16_d16_hi v20, v2 offset:320
	v_mul_f32_e32 v2, v53, v14
	v_bfe_u32 v12, v2, 16, 1
	s_waitcnt lgkmcnt(6)
	v_rcp_f32_e32 v15, v8
	v_add3_u32 v2, v2, v12, s79
	ds_write_b16_d16_hi v20, v2 offset:384
	v_mul_f32_e32 v2, v37, v14
	v_bfe_u32 v12, v2, 16, 1
	v_add3_u32 v2, v2, v12, s79
	ds_write_b16_d16_hi v20, v2 offset:448
	v_mul_f32_e32 v2, v54, v15
	v_bfe_u32 v12, v2, 16, 1
	v_rcp_f32_e32 v16, v9
	v_add3_u32 v2, v2, v12, s79
	ds_write_b16_d16_hi v20, v2 offset:1024
	v_mul_f32_e32 v2, v38, v15
	v_bfe_u32 v12, v2, 16, 1
	v_add3_u32 v2, v2, v12, s79
	ds_write_b16_d16_hi v20, v2 offset:1088
	v_mul_f32_e32 v2, v55, v16
	v_bfe_u32 v12, v2, 16, 1
	v_rcp_f32_e32 v17, v10
	v_add3_u32 v2, v2, v12, s79
	ds_write_b16_d16_hi v20, v2 offset:1152
	v_mul_f32_e32 v2, v39, v16
	v_bfe_u32 v12, v2, 16, 1
	v_add3_u32 v2, v2, v12, s79
	ds_write_b16_d16_hi v20, v2 offset:1216
	v_mul_f32_e32 v2, v56, v17
	v_bfe_u32 v12, v2, 16, 1
	v_rcp_f32_e32 v19, v11
	v_add3_u32 v2, v2, v12, s79
	ds_read_b128 v[4:7], v219 offset:192
	ds_read_b128 v[8:11], v219 offset:224
	ds_write_b16_d16_hi v20, v2 offset:1280
	v_mul_f32_e32 v2, v40, v17
	v_bfe_u32 v12, v2, 16, 1
	v_add3_u32 v2, v2, v12, s79
	ds_write_b16_d16_hi v20, v2 offset:1344
	v_mul_f32_e32 v2, v57, v19
	v_bfe_u32 v12, v2, 16, 1
	s_waitcnt lgkmcnt(3)
; #define LAS __attribute__((address_space(3)))
; __device__ __forceinline__ unsigned f2bf(float f) { unsigned u = __builtin_bit_cast(unsigned, f); return (u + 0x7fffu + ((u >> 16) & 1u)) >> 16; }
; __device__ __forceinline__ unsigned pk2(float lo, float hi) { f32x2_t v = {lo, hi}; bf16x2_t b = __builtin_convertvector(v, bf16x2_t); return __builtin_bit_cast(unsigned, b); }
; __device__ __forceinline__ int crow(int r, int hi) { return (r & 3) + 8 * (r >> 2) + 4 * hi; }
; template <bool NOMAX>
; __device__ __forceinline__ void fox_unit(const AttnCtx& C, int u, LAS unsigned char* lds) {
;     ...
;     float rli[16];
; #pragma unroll
;     for (int r = 0; r < 16; ++r) rli[r] = __builtin_amdgcn_rcpf(wsf[32 + crow(r, hi)]);
;     {
;         LAS bf16* stg = (LAS bf16*)(lds + TF_OST) + wid * 2048;
; #pragma unroll
;         for (int r = 0; r < 16; ++r) { const int orow = crow(r, hi);
; #pragma unroll
;             for (int d0 = 0; d0 < 2; ++d0) stg[orow * 64 + d0 * 32 + r32] = (bf16)f2bf(o[d0][r] * rli[r]); }
;         asm volatile("s_waitcnt lgkmcnt(0)" ::: "memory");
;         int lf = lane; asm volatile("" : "+v"(lf));
;         const size_t rowb = (size_t)(q0 + wid * 32);
; #pragma unroll
;         for (int i = 0; i < 4; ++i) { const int row = i * 8 + (lf >> 3), ch = lf & 7;
;             const v4u sv = *(const LAS v4u*)(stg + row * 64 + ch * 8);
;             const v4u gv = *(const v4u*)(C.GF + (rowb + row) * 512 + h * 64 + ch * 8);
;             v4u ov;
;             ov.x = pk2(__builtin_bit_cast(float, sv.x << 16) * __builtin_bit_cast(float, gv.x << 16), __builtin_bit_cast(float, sv.x & 0xffff0000u) * __builtin_bit_cast(float, gv.x & 0xffff0000u));
;             ov.y = pk2(__builtin_bit_cast(float, sv.y << 16) * __builtin_bit_cast(float, gv.y << 16), __builtin_bit_cast(float, sv.y & 0xffff0000u) * __builtin_bit_cast(float, gv.y & 0xffff0000u));
;             ov.z = pk2(__builtin_bit_cast(float, sv.z << 16) * __builtin_bit_cast(float, gv.z << 16), __builtin_bit_cast(float, sv.z & 0xffff0000u) * __builtin_bit_cast(float, gv.z & 0xffff0000u));
;             ov.w = pk2(__builtin_bit_cast(float, sv.w << 16) * __builtin_bit_cast(float, gv.w << 16), __builtin_bit_cast(float, sv.w & 0xffff0000u) * __builtin_bit_cast(float, gv.w & 0xffff0000u));
;             *(v4u*)(C.MIX + (rowb + row) * 1024 + h * 64 + ch * 8) = ov; }
	v_rcp_f32_e32 v4, v4
	v_add3_u32 v2, v2, v12, s79
	ds_write_b16_d16_hi v20, v2 offset:1408
	v_mul_f32_e32 v2, v41, v19
	v_bfe_u32 v12, v2, 16, 1
	v_add3_u32 v2, v2, v12, s79
	ds_write_b16_d16_hi v20, v2 offset:1472
	v_mul_f32_e32 v2, v58, v4
	v_bfe_u32 v12, v2, 16, 1
	v_rcp_f32_e32 v5, v5
	v_add3_u32 v2, v2, v12, s79
	ds_write_b16_d16_hi v20, v2 offset:2048
	v_mul_f32_e32 v2, v42, v4
	v_bfe_u32 v4, v2, 16, 1
	v_add3_u32 v2, v2, v4, s79
	ds_write_b16_d16_hi v20, v2 offset:2112
	v_mul_f32_e32 v2, v59, v5
	v_bfe_u32 v4, v2, 16, 1
	v_rcp_f32_e32 v6, v6
	v_add3_u32 v2, v2, v4, s79
	ds_write_b16_d16_hi v20, v2 offset:2176
	v_mul_f32_e32 v2, v43, v5
	v_bfe_u32 v4, v2, 16, 1
	v_add3_u32 v2, v2, v4, s79
	ds_write_b16_d16_hi v20, v2 offset:2240
	v_mul_f32_e32 v2, v60, v6
	v_bfe_u32 v4, v2, 16, 1
	v_rcp_f32_e32 v7, v7
	v_add3_u32 v2, v2, v4, s79
	ds_write_b16_d16_hi v20, v2 offset:2304
	v_mul_f32_e32 v2, v44, v6
	v_bfe_u32 v4, v2, 16, 1
	v_add3_u32 v2, v2, v4, s79
	ds_write_b16_d16_hi v20, v2 offset:2368
	v_mul_f32_e32 v2, v61, v7
	v_bfe_u32 v4, v2, 16, 1
	s_waitcnt lgkmcnt(10)
	v_rcp_f32_e32 v8, v8
	v_add3_u32 v2, v2, v4, s79
	ds_write_b16_d16_hi v20, v2 offset:2432
	v_mul_f32_e32 v2, v45, v7
	v_bfe_u32 v4, v2, 16, 1
	v_add3_u32 v2, v2, v4, s79
	ds_write_b16_d16_hi v20, v2 offset:2496
	v_mul_f32_e32 v2, v62, v8
	v_bfe_u32 v4, v2, 16, 1
	v_rcp_f32_e32 v9, v9
	v_add3_u32 v2, v2, v4, s79
	ds_write_b16_d16_hi v20, v2 offset:3072
	v_mul_f32_e32 v2, v46, v8
	v_bfe_u32 v4, v2, 16, 1
	v_add3_u32 v2, v2, v4, s79
	ds_write_b16_d16_hi v20, v2 offset:3136
	v_mul_f32_e32 v2, v63, v9
	v_bfe_u32 v4, v2, 16, 1
	v_rcp_f32_e32 v10, v10
	v_add3_u32 v2, v2, v4, s79
	ds_write_b16_d16_hi v20, v2 offset:3200
	v_mul_f32_e32 v2, v47, v9
	v_bfe_u32 v4, v2, 16, 1
	v_add3_u32 v2, v2, v4, s79
	ds_write_b16_d16_hi v20, v2 offset:3264
	v_mul_f32_e32 v2, v64, v10
	v_bfe_u32 v4, v2, 16, 1
	v_rcp_f32_e32 v11, v11
	v_add3_u32 v2, v2, v4, s79
	ds_write_b16_d16_hi v20, v2 offset:3328
	v_mul_f32_e32 v2, v48, v10
	v_bfe_u32 v4, v2, 16, 1
	v_add3_u32 v2, v2, v4, s79
	ds_write_b16_d16_hi v20, v2 offset:3392
	v_mul_f32_e32 v2, v65, v11
	v_bfe_u32 v4, v2, 16, 1
	v_add3_u32 v2, v2, v4, s79
	ds_write_b16_d16_hi v20, v2 offset:3456
	v_mul_f32_e32 v2, v49, v11
	v_bfe_u32 v4, v2, 16, 1
	v_add3_u32 v2, v2, v4, s79
	ds_write_b16_d16_hi v20, v2 offset:3520
	s_waitcnt lgkmcnt(0)
	v_readlane_b32 s4, v253, 52
	v_ashrrev_i32_e32 v12, 3, v212
	v_ashrrev_i32_e32 v13, 31, v12
	v_lshl_add_u64 v[14:15], v[12:13], 0, s[84:85]
	v_lshlrev_b64 v[4:5], 10, v[14:15]
	v_readlane_b32 s5, v253, 53
	v_lshlrev_b32_e32 v2, 4, v212
	s_mov_b32 s73, s77
	v_lshl_add_u64 v[4:5], s[4:5], 0, v[4:5]
	v_and_b32_e32 v2, 0x70, v2
	v_lshl_add_u64 v[4:5], v[4:5], 0, s[72:73]
	v_lshl_add_u64 v[4:5], v[4:5], 0, v[2:3]
	global_load_dwordx4 v[4:7], v[4:5], off
	v_add_u32_e32 v19, s1, v2
	v_lshl_add_u32 v8, v12, 7, v19
	ds_read_b128 v[8:11], v8
	v_readlane_b32 s2, v253, 28
	v_readlane_b32 s3, v253, 29
	s_waitcnt lgkmcnt(0)
	v_lshlrev_b32_e32 v16, 16, v8
	v_and_b32_e32 v17, 0xffff0000, v8
	v_lshlrev_b32_e32 v8, 16, v9
	v_and_b32_e32 v9, 0xffff0000, v9
	s_waitcnt vmcnt(0)
	v_lshlrev_b32_e32 v20, 16, v4
	v_and_b32_e32 v21, 0xffff0000, v4
	v_pk_mul_f32 v[16:17], v[16:17], v[20:21]
	s_nop 0
	v_cvt_pk_bf16_f32 v4, v16, v17
	v_lshlrev_b32_e32 v16, 16, v5
	v_and_b32_e32 v17, 0xffff0000, v5
	v_pk_mul_f32 v[8:9], v[8:9], v[16:17]
	v_lshlrev_b32_e32 v16, 16, v6
	v_cvt_pk_bf16_f32 v5, v8, v9
	v_lshlrev_b32_e32 v8, 16, v10
	v_and_b32_e32 v9, 0xffff0000, v10
	v_and_b32_e32 v17, 0xffff0000, v6
	v_pk_mul_f32 v[8:9], v[8:9], v[16:17]
	v_lshlrev_b32_e32 v10, 16, v7
	v_cvt_pk_bf16_f32 v6, v8, v9
	v_lshlrev_b32_e32 v8, 16, v11
	v_and_b32_e32 v9, 0xffff0000, v11
	v_and_b32_e32 v11, 0xffff0000, v7
	v_pk_mul_f32 v[8:9], v[8:9], v[10:11]
	s_nop 0
	v_cvt_pk_bf16_f32 v7, v8, v9
	v_lshlrev_b64 v[8:9], 11, v[14:15]
	v_lshl_add_u64 v[8:9], s[2:3], 0, v[8:9]
	v_lshl_add_u64 v[8:9], v[8:9], 0, s[72:73]
	v_lshl_add_u64 v[8:9], v[8:9], 0, v[2:3]
	global_store_dwordx4 v[8:9], v[4:7], off
	v_add_u32_e32 v8, 8, v12
	v_ashrrev_i32_e32 v9, 31, v8
	v_lshl_add_u64 v[14:15], v[8:9], 0, s[84:85]
	v_lshlrev_b64 v[4:5], 10, v[14:15]
	v_lshl_add_u64 v[4:5], s[4:5], 0, v[4:5]
	v_lshl_add_u64 v[4:5], v[4:5], 0, s[72:73]
	v_lshl_add_u64 v[4:5], v[4:5], 0, v[2:3]
	global_load_dwordx4 v[4:7], v[4:5], off
	v_lshl_add_u32 v8, v8, 7, v19
	ds_read_b128 v[8:11], v8
	s_waitcnt lgkmcnt(0)
; #define LAS __attribute__((address_space(3)))
; __device__ __forceinline__ unsigned pk2(float lo, float hi) { f32x2_t v = {lo, hi}; bf16x2_t b = __builtin_convertvector(v, bf16x2_t); return __builtin_bit_cast(unsigned, b); }
; template <bool NOMAX>
; __device__ __forceinline__ void fox_unit(const AttnCtx& C, int u, LAS unsigned char* lds) {
;     ...
;         for (int i = 0; i < 4; ++i) { const int row = i * 8 + (lf >> 3), ch = lf & 7;
;             const v4u sv = *(const LAS v4u*)(stg + row * 64 + ch * 8);
;             const v4u gv = *(const v4u*)(C.GF + (rowb + row) * 512 + h * 64 + ch * 8);
;             v4u ov;
;             ov.x = pk2(__builtin_bit_cast(float, sv.x << 16) * __builtin_bit_cast(float, gv.x << 16), __builtin_bit_cast(float, sv.x & 0xffff0000u) * __builtin_bit_cast(float, gv.x & 0xffff0000u));
;             ov.y = pk2(__builtin_bit_cast(float, sv.y << 16) * __builtin_bit_cast(float, gv.y << 16), __builtin_bit_cast(float, sv.y & 0xffff0000u) * __builtin_bit_cast(float, gv.y & 0xffff0000u));
;             ov.z = pk2(__builtin_bit_cast(float, sv.z << 16) * __builtin_bit_cast(float, gv.z << 16), __builtin_bit_cast(float, sv.z & 0xffff0000u) * __builtin_bit_cast(float, gv.z & 0xffff0000u));
;             ov.w = pk2(__builtin_bit_cast(float, sv.w << 16) * __builtin_bit_cast(float, gv.w << 16), __builtin_bit_cast(float, sv.w & 0xffff0000u) * __builtin_bit_cast(float, gv.w & 0xffff0000u));
;             *(v4u*)(C.MIX + (rowb + row) * 1024 + h * 64 + ch * 8) = ov; }
; template <int KIND>
; __device__ __forceinline__ void attn_queue(const AttnCtx& C, unsigned* head, int nunits, LAS unsigned char* lds) {
;     ...
;         __syncthreads();
;         if (threadIdx.x == 0) slot[0] = __hip_atomic_fetch_add(head, 1u, __ATOMIC_RELAXED, __HIP_MEMORY_SCOPE_AGENT);
	v_lshlrev_b32_e32 v16, 16, v8
	v_and_b32_e32 v17, 0xffff0000, v8
	v_lshlrev_b32_e32 v8, 16, v9
	v_and_b32_e32 v9, 0xffff0000, v9
	s_waitcnt vmcnt(0)
	v_lshlrev_b32_e32 v20, 16, v4
	v_and_b32_e32 v21, 0xffff0000, v4
	v_pk_mul_f32 v[16:17], v[16:17], v[20:21]
	s_nop 0
	v_cvt_pk_bf16_f32 v4, v16, v17
	v_lshlrev_b32_e32 v16, 16, v5
	v_and_b32_e32 v17, 0xffff0000, v5
	v_pk_mul_f32 v[8:9], v[8:9], v[16:17]
	v_lshlrev_b32_e32 v16, 16, v6
	v_cvt_pk_bf16_f32 v5, v8, v9
	v_lshlrev_b32_e32 v8, 16, v10
	v_and_b32_e32 v9, 0xffff0000, v10
	v_and_b32_e32 v17, 0xffff0000, v6
	v_pk_mul_f32 v[8:9], v[8:9], v[16:17]
	v_lshlrev_b32_e32 v10, 16, v7
	v_cvt_pk_bf16_f32 v6, v8, v9
	v_lshlrev_b32_e32 v8, 16, v11
	v_and_b32_e32 v9, 0xffff0000, v11
	v_and_b32_e32 v11, 0xffff0000, v7
	v_pk_mul_f32 v[8:9], v[8:9], v[10:11]
	s_nop 0
	v_cvt_pk_bf16_f32 v7, v8, v9
	v_lshlrev_b64 v[8:9], 11, v[14:15]
	v_lshl_add_u64 v[8:9], s[2:3], 0, v[8:9]
	v_lshl_add_u64 v[8:9], v[8:9], 0, s[72:73]
	v_lshl_add_u64 v[8:9], v[8:9], 0, v[2:3]
	global_store_dwordx4 v[8:9], v[4:7], off
	v_add_u32_e32 v8, 16, v12
	v_ashrrev_i32_e32 v9, 31, v8
	v_lshl_add_u64 v[14:15], v[8:9], 0, s[84:85]
	v_lshlrev_b64 v[4:5], 10, v[14:15]
	v_lshl_add_u64 v[4:5], s[4:5], 0, v[4:5]
	v_lshl_add_u64 v[4:5], v[4:5], 0, s[72:73]
	v_lshl_add_u64 v[4:5], v[4:5], 0, v[2:3]
	global_load_dwordx4 v[4:7], v[4:5], off
	v_lshl_add_u32 v8, v8, 7, v19
	ds_read_b128 v[8:11], v8
	v_lshlrev_b64 v[14:15], 11, v[14:15]
	s_waitcnt lgkmcnt(0)
	v_lshlrev_b32_e32 v16, 16, v8
	v_and_b32_e32 v17, 0xffff0000, v8
	v_lshlrev_b32_e32 v8, 16, v9
	v_and_b32_e32 v9, 0xffff0000, v9
	v_lshlrev_b32_e32 v20, 16, v10
	v_and_b32_e32 v21, 0xffff0000, v10
	v_lshlrev_b32_e32 v10, 16, v11
	v_and_b32_e32 v11, 0xffff0000, v11
	s_waitcnt vmcnt(0)
	v_lshlrev_b32_e32 v22, 16, v4
	v_and_b32_e32 v23, 0xffff0000, v4
	v_lshlrev_b32_e32 v4, 16, v5
	v_and_b32_e32 v5, 0xffff0000, v5
	v_pk_mul_f32 v[8:9], v[8:9], v[4:5]
	v_lshlrev_b32_e32 v24, 16, v6
	v_and_b32_e32 v25, 0xffff0000, v6
	v_lshlrev_b32_e32 v6, 16, v7
	v_and_b32_e32 v7, 0xffff0000, v7
	v_cvt_pk_bf16_f32 v5, v8, v9
	v_lshl_add_u64 v[8:9], s[2:3], 0, v[14:15]
	v_pk_mul_f32 v[16:17], v[16:17], v[22:23]
	v_pk_mul_f32 v[20:21], v[20:21], v[24:25]
	v_pk_mul_f32 v[10:11], v[10:11], v[6:7]
	v_lshl_add_u64 v[8:9], v[8:9], 0, s[72:73]
	v_cvt_pk_bf16_f32 v4, v16, v17
	v_cvt_pk_bf16_f32 v6, v20, v21
	v_cvt_pk_bf16_f32 v7, v10, v11
	v_lshl_add_u64 v[8:9], v[8:9], 0, v[2:3]
	global_store_dwordx4 v[8:9], v[4:7], off
	v_add_u32_e32 v8, 24, v12
	v_ashrrev_i32_e32 v9, 31, v8
	v_lshl_add_u64 v[12:13], v[8:9], 0, s[84:85]
	v_lshlrev_b64 v[4:5], 10, v[12:13]
	v_lshl_add_u64 v[4:5], s[4:5], 0, v[4:5]
	v_lshl_add_u64 v[4:5], v[4:5], 0, s[72:73]
	v_lshl_add_u64 v[4:5], v[4:5], 0, v[2:3]
	global_load_dwordx4 v[4:7], v[4:5], off
	v_lshl_add_u32 v8, v8, 7, v19
	ds_read_b128 v[8:11], v8
	v_lshlrev_b64 v[12:13], 11, v[12:13]
	v_lshl_add_u64 v[12:13], s[2:3], 0, v[12:13]
	v_lshl_add_u64 v[12:13], v[12:13], 0, s[72:73]
	s_mov_b64 s[2:3], 0
	s_waitcnt lgkmcnt(0)
	v_lshlrev_b32_e32 v14, 16, v8
	v_and_b32_e32 v15, 0xffff0000, v8
	v_lshlrev_b32_e32 v8, 16, v9
	v_and_b32_e32 v9, 0xffff0000, v9
	v_lshlrev_b32_e32 v16, 16, v10
	v_and_b32_e32 v17, 0xffff0000, v10
	v_lshlrev_b32_e32 v10, 16, v11
	v_and_b32_e32 v11, 0xffff0000, v11
	s_waitcnt vmcnt(0)
	v_lshlrev_b32_e32 v20, 16, v4
	v_and_b32_e32 v21, 0xffff0000, v4
	v_lshlrev_b32_e32 v4, 16, v5
	v_and_b32_e32 v5, 0xffff0000, v5
	v_lshlrev_b32_e32 v22, 16, v6
	v_and_b32_e32 v23, 0xffff0000, v6
	v_lshlrev_b32_e32 v6, 16, v7
	v_and_b32_e32 v7, 0xffff0000, v7
	v_pk_mul_f32 v[14:15], v[14:15], v[20:21]
	v_pk_mul_f32 v[8:9], v[8:9], v[4:5]
	v_pk_mul_f32 v[16:17], v[16:17], v[22:23]
	v_pk_mul_f32 v[10:11], v[10:11], v[6:7]
	v_cvt_pk_bf16_f32 v4, v14, v15
	v_cvt_pk_bf16_f32 v5, v8, v9
	v_cvt_pk_bf16_f32 v6, v16, v17
	v_cvt_pk_bf16_f32 v7, v10, v11
	v_lshl_add_u64 v[8:9], v[12:13], 0, v[2:3]
	global_store_dwordx4 v[8:9], v[4:7], off
	s_mov_b64 s[98:99], exec
	v_readlane_b32 s0, v253, 26
	v_readlane_b32 s1, v253, 27
	s_and_b64 s[0:1], s[98:99], s[0:1]
	s_mov_b64 exec, s[0:1]
	s_cbranch_execz .Lpp_f_skipb
	v_readlane_b32 s94, v252, 16
	v_readlane_b32 s95, v252, 17
	v_mov_b32_e32 v254, 0
	v_mov_b32_e32 v4, 1
	s_nop 4
	global_atomic_add v4, v254, v4, s[94:95] offset:1024 sc0
